# gla_scan: two chunks per workgroup barrier, their gate math interleaved instruction by instruction (32 barriers per unit instead of 64)
# baseline (speedup 1.0000x reference)
;     ...
;     for (int u = vb; u < 256; u += nb) {
;         const int b = u >> 5, hh = (u >> 3) & 3, ksl = u & 7;
;         const int kc0 = hh * 128 + ksl * 16 + 2 * w;
;         float wa[2][16], bb[2];
; #pragma unroll
;         for (int e = 0; e < 2; ++e) { bb[e] = ba[kc0 + e];
; #pragma unroll
;             for (int jj = 0; jj < 16; ++jj) wa[e][jj] = w2[jj * 512 + kc0 + e]; }
;         f32x4 acc[2];
; #pragma unroll
;         for (int e = 0; e < 2; ++e) acc[e] = (f32x4){0.f, 0.f, 0.f, 0.f};
;         __syncthreads();
;         f32x4 a4n[4]; unsigned krawn; bf16x8 vfrn[2][2];
;         auto ldchunk = [&](int n) {
;             const int tok = b * 4096 + n * 64 + l;
; #pragma unroll
;             for (int q = 0; q < 4; ++q) a4n[q] = *(const f32x4*)(GA + (size_t)tok * 16 + 4 * q);
;             krawn = *(const unsigned*)(GK + (size_t)tok * 512 + kc0);
; #pragma unroll
;             for (int e = 0; e < 2; ++e)
; #pragma unroll
;                 for (int ks = 0; ks < 2; ++ks)
;                     vfrn[e][ks] = *(const bf16x8*)(GVT + ((size_t)(b * 1024 + hh * 256 + (2 * w + e) * 16 + (l & 15))) * 4096 + n * 64 + ks * 32 + (l >> 4) * 8);
;         };
;         ldchunk(0);
.LBB0_418:
	s_bfe_u32 s57, s56, 0x20003
	s_lshl_b32 s21, s56, 4
	s_and_b32 s21, s21, 0x70
	s_lshl_b32 s20, s57, 7
	s_or_b32 s20, s20, s21
	s_ashr_i32 s28, s56, 5
	v_mov_b32_e32 v220, 0xbfb8aa3b
	v_mov_b32_e32 v222, 1.0
	v_mov_b32_e32 v223, 1.0
	v_mov_b32_e32 v224, 0x3f317217
	v_mov_b32_e32 v225, 0x3f317217
	v_mov_b32_e32 v226, 0x3377d1cf
	v_mov_b32_e32 v227, 0x3377d1cf
	v_mov_b32_e32 v228, 0x3fb8aa3b
	v_mov_b32_e32 v229, 0x3fb8aa3b
	v_mov_b32_e32 v214, 0x3d800000
	v_mov_b32_e32 v215, 0x3d800000
	v_lshrrev_b32_e32 v27, 6, v249
	v_lshrrev_b32_e32 v9, 3, v160
	v_lshl_add_u32 v8, v27, 3, v9
	v_and_b32_e32 v10, 7, v160
	v_lshlrev_b32_e32 v230, 3, v160
	v_lshl_add_u32 v230, v27, 9, v230
	v_lshlrev_b32_e32 v231, 2, v10
	v_lshl_add_u32 v231, v8, 10, v231
	v_mul_u32_u24_e32 v28, 0x50, v8
	v_lshl_add_u32 v28, v10, 3, v28
	v_add_u32_e32 v28, 0x4010, v28
	v_mul_u32_u24_e32 v29, 0x50, v160
	v_add_u32_e32 v29, 0x4010, v29
	v_mul_u32_u24_e32 v30, 0x104, v10
	v_lshl_add_u32 v30, v8, 2, v30
	v_add_u32_e32 v30, 0xa010, v30
	v_mul_u32_u24_e32 v31, 0x104, v27
	v_lshl_add_u32 v31, v160, 2, v31
	v_add_u32_e32 v31, 0xa010, v31
	v_lshrrev_b32_e32 v11, 4, v160
	v_lshlrev_b32_e32 v232, 6, v72
	v_lshl_add_u32 v232, v11, 4, v232
	v_add_u32_e32 v233, 0x4000, v232
	v_lshrrev_b32_e32 v12, 2, v72
	v_lshlrev_b32_e32 v234, 10, v12
	v_and_b32_e32 v12, 3, v72
	v_lshl_add_u32 v234, v12, 5, v234
	v_lshl_add_u32 v234, v11, 3, v234
	v_add_u32_e32 v235, 0x1000, v234
	v_add_u32_e32 v13, s20, v161
	v_lshlrev_b32_e32 v13, 2, v13
	s_mov_b64 s[50:51], s[8:9]
	global_load_dwordx2 v[86:87], v13, s[50:51]
	global_load_dwordx2 v[88:89], v13, s[50:51] offset:2048
	s_add_u32 s50, s50, 0x1000
	s_addc_u32 s51, s51, 0
	global_load_dwordx2 v[90:91], v13, s[50:51]
	global_load_dwordx2 v[92:93], v13, s[50:51] offset:2048
	s_add_u32 s50, s50, 0x1000
	s_addc_u32 s51, s51, 0
	global_load_dwordx2 v[94:95], v13, s[50:51]
	global_load_dwordx2 v[96:97], v13, s[50:51] offset:2048
	s_add_u32 s50, s50, 0x1000
	s_addc_u32 s51, s51, 0
	global_load_dwordx2 v[98:99], v13, s[50:51]
	global_load_dwordx2 v[100:101], v13, s[50:51] offset:2048
	s_add_u32 s50, s50, 0x1000
	s_addc_u32 s51, s51, 0
	global_load_dwordx2 v[102:103], v13, s[50:51]
	global_load_dwordx2 v[104:105], v13, s[50:51] offset:2048
	s_add_u32 s50, s50, 0x1000
	s_addc_u32 s51, s51, 0
	global_load_dwordx2 v[106:107], v13, s[50:51]
	global_load_dwordx2 v[108:109], v13, s[50:51] offset:2048
	s_add_u32 s50, s50, 0x1000
	s_addc_u32 s51, s51, 0
	global_load_dwordx2 v[110:111], v13, s[50:51]
	global_load_dwordx2 v[112:113], v13, s[50:51] offset:2048
	s_add_u32 s50, s50, 0x1000
	s_addc_u32 s51, s51, 0
	global_load_dwordx2 v[114:115], v13, s[50:51]
	global_load_dwordx2 v[116:117], v13, s[50:51] offset:2048
	s_add_u32 s50, s50, 0x1000
	s_addc_u32 s51, s51, 0
	global_load_dwordx2 v[118:119], v13, s[18:19]
	v_readlane_b32 s26, v253, 13
	v_readlane_b32 s27, v253, 14
	v_readlane_b32 s58, v254, 26
	v_readlane_b32 s59, v254, 27
	v_readlane_b32 s34, v253, 11
	v_readlane_b32 s35, v253, 12
	v_readlane_b32 s100, v254, 28
	v_readlane_b32 s101, v254, 29
	s_lshl_b32 s52, s28, 18
	s_add_u32 s26, s26, s52
	s_addc_u32 s27, s27, 0
	s_lshl_b32 s52, s28, 22
	s_lshl_b32 s53, s20, 1
	s_add_u32 s52, s52, s53
	s_add_u32 s58, s58, s52
	s_addc_u32 s59, s59, 0
	s_lshl_b32 s52, s28, 23
	s_lshl_b32 s53, s57, 21
	s_add_u32 s52, s52, s53
	s_add_u32 s34, s34, s52
	s_addc_u32 s35, s35, 0
	s_lshl_b32 s52, s28, 8
	s_or_b32 s52, s52, s57
	s_lshl_b32 s52, s52, 16
	s_lshl_b32 s53, s21, 3
	s_add_u32 s52, s52, s53
	s_add_u32 s100, s100, s52
	s_addc_u32 s101, s101, 0
	v_mov_b32_e32 v0, 0
	v_mov_b32_e32 v1, 0
	v_mov_b32_e32 v2, 0
	v_mov_b32_e32 v3, 0
	v_mov_b32_e32 v4, 0
	v_mov_b32_e32 v5, 0
	v_mov_b32_e32 v6, 0
	v_mov_b32_e32 v7, 0
	s_barrier
	global_load_dwordx2 v[146:147], v230, s[26:27]
	global_load_dword v150, v231, s[58:59]
	s_add_u32 s26, s26, 0x1000
	s_addc_u32 s27, s27, 0
	s_add_u32 s58, s58, 0x10000
	s_addc_u32 s59, s59, 0
	global_load_dwordx2 v[148:149], v230, s[26:27]
	global_load_dword v151, v231, s[58:59]
	s_add_u32 s26, s26, 0x1000
	s_addc_u32 s27, s27, 0
	s_add_u32 s58, s58, 0x10000
	s_addc_u32 s59, s59, 0
	global_load_dwordx2 v[152:153], v230, s[26:27]
	global_load_dword v158, v231, s[58:59]
	s_add_u32 s26, s26, 0x1000
	s_addc_u32 s27, s27, 0
	s_add_u32 s58, s58, 0x10000
	s_addc_u32 s59, s59, 0
	global_load_dwordx2 v[166:167], v230, s[26:27]
	global_load_dword v159, v231, s[58:59]
	s_add_u32 s26, s26, 0x1000
	s_addc_u32 s27, s27, 0
	s_add_u32 s58, s58, 0x10000
	s_addc_u32 s59, s59, 0
	s_waitcnt vmcnt(0)
	ds_write_b64 v28, v[146:147] offset:0
	ds_write_b32 v30, v150 offset:0
	ds_write_b64 v28, v[148:149] offset:5120
	ds_write_b32 v30, v151 offset:2080
	s_waitcnt lgkmcnt(0)
	s_barrier
; DI float bf2f(unsigned x) { return __uint_as_float(x << 16); }
;     ...
;         auto ldchunk = [&](int n) {
;             const int tok = b * 4096 + n * 64 + l;
; #pragma unroll
;             for (int q = 0; q < 4; ++q) a4n[q] = *(const f32x4*)(GA + (size_t)tok * 16 + 4 * q);
;             krawn = *(const unsigned*)(GK + (size_t)tok * 512 + kc0);
; #pragma unroll
;             for (int e = 0; e < 2; ++e)
; #pragma unroll
;                 for (int ks = 0; ks < 2; ++ks)
;                     vfrn[e][ks] = *(const bf16x8*)(GVT + ((size_t)(b * 1024 + hh * 256 + (2 * w + e) * 16 + (l & 15))) * 4096 + n * 64 + ks * 32 + (l >> 4) * 8);
;         };
;         ldchunk(0);
;         for (int n = 0; n < 64; ++n) {
;             const int buf = n & 1;
;             f32x4 a4[4]; bf16x8 vfr[2][2];
; #pragma unroll
;             for (int q = 0; q < 4; ++q) a4[q] = a4n[q];
;             const unsigned kraw = krawn;
; #pragma unroll
;             for (int e = 0; e < 2; ++e)
; #pragma unroll
;                 for (int ks = 0; ks < 2; ++ks) vfr[e][ks] = vfrn[e][ks];
;             if (n + 1 < 64) ldchunk(n + 1);
;             float cum[2];
; #pragma unroll
;             for (int e = 0; e < 2; ++e) {
;                 float z = bb[e];
; #pragma unroll
;                 for (int q = 0; q < 4; ++q) { z += a4[q].x * wa[e][4 * q] + a4[q].y * wa[e][4 * q + 1] + a4[q].z * wa[e][4 * q + 2] + a4[q].w * wa[e][4 * q + 3]; }
;                 cum[e] = (fminf(z, 0.f) - __logf(1.f + __expf(-fabsf(z)))) * (1.f / 16.f);
;             }
; #pragma unroll
;             for (int o = 1; o < 64; o <<= 1) {
;                 const float t0 = __shfl_up(cum[0], o), t1 = __shfl_up(cum[1], o);
;                 if (l >= o) { cum[0] += t0; cum[1] += t1; }
;             }
;             const float tot0 = __shfl(cum[0], 63), tot1 = __shfl(cum[1], 63);
;             kdl[(buf * 16 + 2 * w) * 64 + l] = f2bf(bf2f(kraw & 0xffffu) * __expf(tot0 - cum[0]));
;             kdl[(buf * 16 + 2 * w + 1) * 64 + l] = f2bf(bf2f(kraw >> 16) * __expf(tot1 - cum[1]));
;             if (l == 0) { decl[buf * 16 + 2 * w] = __expf(tot0); decl[buf * 16 + 2 * w + 1] = __expf(tot1); }
;             __syncthreads();
;             const f32x4 d4 = *(const f32x4*)(decl + buf * 16 + (l >> 4) * 4);
; #pragma unroll
;             for (int e = 0; e < 2; ++e) acc[e] = acc[e] * d4;
; #pragma unroll
;             for (int ks = 0; ks < 2; ++ks) {
	ds_read_b128 v[8:11], v29 offset:0
	ds_read_b128 v[12:15], v29 offset:16
	ds_read_b128 v[16:19], v29 offset:32
	ds_read_b128 v[20:23], v29 offset:48
	ds_read_b32 v24, v31 offset:0
	ds_read_b128 v[32:35], v29 offset:5120
	ds_read_b128 v[36:39], v29 offset:5136
	ds_read_b128 v[40:43], v29 offset:5152
	ds_read_b128 v[44:47], v29 offset:5168
	ds_read_b32 v25, v31 offset:2080
	global_load_dwordx2 v[146:147], v230, s[26:27]
	global_load_dword v150, v231, s[58:59]
	s_add_u32 s26, s26, 0x1000
	s_addc_u32 s27, s27, 0
	s_add_u32 s58, s58, 0x10000
	s_addc_u32 s59, s59, 0
	global_load_dwordx2 v[148:149], v230, s[26:27]
	global_load_dword v151, v231, s[58:59]
	s_add_u32 s26, s26, 0x1000
	s_addc_u32 s27, s27, 0
	s_add_u32 s58, s58, 0x10000
	s_addc_u32 s59, s59, 0
	global_load_dwordx4 v[178:181], v232, s[34:35]
	global_load_dwordx4 v[182:185], v233, s[34:35]
	global_load_dwordx4 v[186:189], v232, s[34:35] offset:1024
	global_load_dwordx4 v[190:193], v233, s[34:35] offset:1024
	s_add_u32 s34, s34, 0x8000
	s_addc_u32 s35, s35, 0
	global_load_dwordx4 v[194:197], v232, s[34:35]
	global_load_dwordx4 v[198:201], v233, s[34:35]
	global_load_dwordx4 v[202:205], v232, s[34:35] offset:1024
	global_load_dwordx4 v[206:209], v233, s[34:35] offset:1024
	s_add_u32 s34, s34, 0x8000
	s_addc_u32 s35, s35, 0
	s_waitcnt lgkmcnt(0)
	v_pk_fma_f32 v[64:65], v[8:9], v[86:87], v[118:119] op_sel:[0,0,0] op_sel_hi:[0,1,1]
	v_pk_fma_f32 v[138:139], v[32:33], v[86:87], v[118:119] op_sel:[0,0,0] op_sel_hi:[0,1,1]
	v_pk_mul_f32 v[66:67], v[16:17], v[102:103] op_sel:[0,0] op_sel_hi:[0,1]
	v_pk_mul_f32 v[140:141], v[40:41], v[102:103] op_sel:[0,0] op_sel_hi:[0,1]
	v_pk_fma_f32 v[64:65], v[8:9], v[88:89], v[64:65] op_sel:[1,0,0] op_sel_hi:[1,1,1]
	v_pk_fma_f32 v[138:139], v[32:33], v[88:89], v[138:139] op_sel:[1,0,0] op_sel_hi:[1,1,1]
	v_pk_fma_f32 v[66:67], v[16:17], v[104:105], v[66:67] op_sel:[1,0,0] op_sel_hi:[1,1,1]
	v_pk_fma_f32 v[140:141], v[40:41], v[104:105], v[140:141] op_sel:[1,0,0] op_sel_hi:[1,1,1]
	v_pk_fma_f32 v[64:65], v[10:11], v[90:91], v[64:65] op_sel:[0,0,0] op_sel_hi:[0,1,1]
	v_pk_fma_f32 v[138:139], v[34:35], v[90:91], v[138:139] op_sel:[0,0,0] op_sel_hi:[0,1,1]
	v_pk_fma_f32 v[66:67], v[18:19], v[106:107], v[66:67] op_sel:[0,0,0] op_sel_hi:[0,1,1]
	v_pk_fma_f32 v[140:141], v[42:43], v[106:107], v[140:141] op_sel:[0,0,0] op_sel_hi:[0,1,1]
	v_pk_fma_f32 v[64:65], v[10:11], v[92:93], v[64:65] op_sel:[1,0,0] op_sel_hi:[1,1,1]
	v_pk_fma_f32 v[138:139], v[34:35], v[92:93], v[138:139] op_sel:[1,0,0] op_sel_hi:[1,1,1]
	v_pk_fma_f32 v[66:67], v[18:19], v[108:109], v[66:67] op_sel:[1,0,0] op_sel_hi:[1,1,1]
	v_pk_fma_f32 v[140:141], v[42:43], v[108:109], v[140:141] op_sel:[1,0,0] op_sel_hi:[1,1,1]
	v_pk_fma_f32 v[64:65], v[12:13], v[94:95], v[64:65] op_sel:[0,0,0] op_sel_hi:[0,1,1]
	v_pk_fma_f32 v[138:139], v[36:37], v[94:95], v[138:139] op_sel:[0,0,0] op_sel_hi:[0,1,1]
	v_pk_fma_f32 v[66:67], v[20:21], v[110:111], v[66:67] op_sel:[0,0,0] op_sel_hi:[0,1,1]
	v_pk_fma_f32 v[140:141], v[44:45], v[110:111], v[140:141] op_sel:[0,0,0] op_sel_hi:[0,1,1]
	v_pk_fma_f32 v[64:65], v[12:13], v[96:97], v[64:65] op_sel:[1,0,0] op_sel_hi:[1,1,1]
	v_pk_fma_f32 v[138:139], v[36:37], v[96:97], v[138:139] op_sel:[1,0,0] op_sel_hi:[1,1,1]
	v_pk_fma_f32 v[66:67], v[20:21], v[112:113], v[66:67] op_sel:[1,0,0] op_sel_hi:[1,1,1]
	v_pk_fma_f32 v[140:141], v[44:45], v[112:113], v[140:141] op_sel:[1,0,0] op_sel_hi:[1,1,1]
	v_pk_fma_f32 v[64:65], v[14:15], v[98:99], v[64:65] op_sel:[0,0,0] op_sel_hi:[0,1,1]
	v_pk_fma_f32 v[138:139], v[38:39], v[98:99], v[138:139] op_sel:[0,0,0] op_sel_hi:[0,1,1]
	v_pk_fma_f32 v[66:67], v[22:23], v[114:115], v[66:67] op_sel:[0,0,0] op_sel_hi:[0,1,1]
	v_pk_fma_f32 v[140:141], v[46:47], v[114:115], v[140:141] op_sel:[0,0,0] op_sel_hi:[0,1,1]
	v_pk_fma_f32 v[64:65], v[14:15], v[100:101], v[64:65] op_sel:[1,0,0] op_sel_hi:[1,1,1]
	v_pk_fma_f32 v[138:139], v[38:39], v[100:101], v[138:139] op_sel:[1,0,0] op_sel_hi:[1,1,1]
	v_pk_fma_f32 v[66:67], v[22:23], v[116:117], v[66:67] op_sel:[1,0,0] op_sel_hi:[1,1,1]
	v_pk_fma_f32 v[140:141], v[46:47], v[116:117], v[140:141] op_sel:[1,0,0] op_sel_hi:[1,1,1]
	v_pk_add_f32 v[64:65], v[64:65], v[66:67]
	v_pk_add_f32 v[138:139], v[138:139], v[140:141]
	v_mul_f32_e64 v66, |v64|, v220
	v_mul_f32_e64 v140, |v138|, v220
	v_mul_f32_e64 v67, |v65|, v220
	v_mul_f32_e64 v141, |v139|, v220
	v_exp_f32_e32 v66, v66
	v_exp_f32_e32 v140, v140
	v_exp_f32_e32 v67, v67
	v_exp_f32_e32 v141, v141
	v_min_f32_e32 v68, 0, v64
	v_min_f32_e32 v142, 0, v138
	v_min_f32_e32 v69, 0, v65
	v_min_f32_e32 v143, 0, v139
	v_pk_add_f32 v[66:67], v[66:67], v[222:223]
	v_pk_add_f32 v[140:141], v[140:141], v[222:223]
	v_log_f32_e32 v64, v66
	v_log_f32_e32 v138, v140
	v_log_f32_e32 v65, v67
	v_log_f32_e32 v139, v141
	v_pk_mul_f32 v[66:67], v[64:65], v[224:225]
	v_pk_mul_f32 v[140:141], v[138:139], v[224:225]
	v_pk_fma_f32 v[70:71], v[64:65], v[224:225], v[66:67] neg_lo:[0,0,1] neg_hi:[0,0,1]
	v_pk_fma_f32 v[144:145], v[138:139], v[224:225], v[140:141] neg_lo:[0,0,1] neg_hi:[0,0,1]
	v_pk_fma_f32 v[70:71], v[64:65], v[226:227], v[70:71]
	v_pk_fma_f32 v[144:145], v[138:139], v[226:227], v[144:145]
	v_pk_fma_f32 v[70:71], v[64:65], v[224:225], v[70:71]
	v_pk_fma_f32 v[144:145], v[138:139], v[224:225], v[144:145]
	v_pk_add_f32 v[68:69], v[68:69], v[70:71] neg_lo:[0,1] neg_hi:[0,1]
	v_pk_add_f32 v[142:143], v[142:143], v[144:145] neg_lo:[0,1] neg_hi:[0,1]
	v_pk_mul_f32 v[68:69], v[68:69], v[214:215]
	v_pk_mul_f32 v[142:143], v[142:143], v[214:215]
	s_nop 0
	v_add_f32_dpp v68, v68, v68 row_shr:1 row_mask:0xf bank_mask:0xf
	v_add_f32_dpp v142, v142, v142 row_shr:1 row_mask:0xf bank_mask:0xf
; DI float bf2f(unsigned x) { return __uint_as_float(x << 16); }
;     ...
;         auto ldchunk = [&](int n) {
;             const int tok = b * 4096 + n * 64 + l;
; #pragma unroll
;             for (int q = 0; q < 4; ++q) a4n[q] = *(const f32x4*)(GA + (size_t)tok * 16 + 4 * q);
;             krawn = *(const unsigned*)(GK + (size_t)tok * 512 + kc0);
; #pragma unroll
;             for (int e = 0; e < 2; ++e)
; #pragma unroll
;                 for (int ks = 0; ks < 2; ++ks)
;                     vfrn[e][ks] = *(const bf16x8*)(GVT + ((size_t)(b * 1024 + hh * 256 + (2 * w + e) * 16 + (l & 15))) * 4096 + n * 64 + ks * 32 + (l >> 4) * 8);
;         };
;         ldchunk(0);
;         for (int n = 0; n < 64; ++n) {
;             const int buf = n & 1;
;             f32x4 a4[4]; bf16x8 vfr[2][2];
; #pragma unroll
;             for (int q = 0; q < 4; ++q) a4[q] = a4n[q];
;             const unsigned kraw = krawn;
; #pragma unroll
;             for (int e = 0; e < 2; ++e)
; #pragma unroll
;                 for (int ks = 0; ks < 2; ++ks) vfr[e][ks] = vfrn[e][ks];
;             if (n + 1 < 64) ldchunk(n + 1);
;             float cum[2];
; #pragma unroll
;             for (int e = 0; e < 2; ++e) {
;                 float z = bb[e];
; #pragma unroll
;                 for (int q = 0; q < 4; ++q) { z += a4[q].x * wa[e][4 * q] + a4[q].y * wa[e][4 * q + 1] + a4[q].z * wa[e][4 * q + 2] + a4[q].w * wa[e][4 * q + 3]; }
;                 cum[e] = (fminf(z, 0.f) - __logf(1.f + __expf(-fabsf(z)))) * (1.f / 16.f);
;             }
; #pragma unroll
;             for (int o = 1; o < 64; o <<= 1) {
;                 const float t0 = __shfl_up(cum[0], o), t1 = __shfl_up(cum[1], o);
;                 if (l >= o) { cum[0] += t0; cum[1] += t1; }
;             }
;             const float tot0 = __shfl(cum[0], 63), tot1 = __shfl(cum[1], 63);
;             kdl[(buf * 16 + 2 * w) * 64 + l] = f2bf(bf2f(kraw & 0xffffu) * __expf(tot0 - cum[0]));
;             kdl[(buf * 16 + 2 * w + 1) * 64 + l] = f2bf(bf2f(kraw >> 16) * __expf(tot1 - cum[1]));
;             if (l == 0) { decl[buf * 16 + 2 * w] = __expf(tot0); decl[buf * 16 + 2 * w + 1] = __expf(tot1); }
;             __syncthreads();
;             const f32x4 d4 = *(const f32x4*)(decl + buf * 16 + (l >> 4) * 4);
; #pragma unroll
;             for (int e = 0; e < 2; ++e) acc[e] = acc[e] * d4;
; #pragma unroll
;             for (int ks = 0; ks < 2; ++ks) {
	v_add_f32_dpp v69, v69, v69 row_shr:1 row_mask:0xf bank_mask:0xf
	v_add_f32_dpp v143, v143, v143 row_shr:1 row_mask:0xf bank_mask:0xf
	v_add_f32_dpp v68, v68, v68 row_shr:2 row_mask:0xf bank_mask:0xf
	v_add_f32_dpp v142, v142, v142 row_shr:2 row_mask:0xf bank_mask:0xf
	v_add_f32_dpp v69, v69, v69 row_shr:2 row_mask:0xf bank_mask:0xf
	v_add_f32_dpp v143, v143, v143 row_shr:2 row_mask:0xf bank_mask:0xf
	v_add_f32_dpp v68, v68, v68 row_shr:4 row_mask:0xf bank_mask:0xf
	v_add_f32_dpp v142, v142, v142 row_shr:4 row_mask:0xf bank_mask:0xf
	v_add_f32_dpp v69, v69, v69 row_shr:4 row_mask:0xf bank_mask:0xf
	v_add_f32_dpp v143, v143, v143 row_shr:4 row_mask:0xf bank_mask:0xf
	v_add_f32_dpp v68, v68, v68 row_shr:8 row_mask:0xf bank_mask:0xf
	v_add_f32_dpp v142, v142, v142 row_shr:8 row_mask:0xf bank_mask:0xf
	v_add_f32_dpp v69, v69, v69 row_shr:8 row_mask:0xf bank_mask:0xf
	v_add_f32_dpp v143, v143, v143 row_shr:8 row_mask:0xf bank_mask:0xf
	v_add_f32_dpp v68, v68, v68 row_bcast:15 row_mask:0xa bank_mask:0xf
	v_add_f32_dpp v142, v142, v142 row_bcast:15 row_mask:0xa bank_mask:0xf
	v_add_f32_dpp v69, v69, v69 row_bcast:15 row_mask:0xa bank_mask:0xf
	v_add_f32_dpp v143, v143, v143 row_bcast:15 row_mask:0xa bank_mask:0xf
	v_add_f32_dpp v68, v68, v68 row_bcast:31 row_mask:0xc bank_mask:0xf
	v_add_f32_dpp v142, v142, v142 row_bcast:31 row_mask:0xc bank_mask:0xf
	v_add_f32_dpp v69, v69, v69 row_bcast:31 row_mask:0xc bank_mask:0xf
	v_add_f32_dpp v143, v143, v143 row_bcast:31 row_mask:0xc bank_mask:0xf
	v_readlane_b32 s98, v68, 63
	v_readlane_b32 s52, v142, 63
	v_readlane_b32 s99, v69, 63
	v_readlane_b32 s53, v143, 63
	s_nop 0
	v_pk_add_f32 v[66:67], s[98:99], v[68:69] neg_lo:[0,1] neg_hi:[0,1]
	v_pk_add_f32 v[140:141], s[52:53], v[142:143] neg_lo:[0,1] neg_hi:[0,1]
	v_mul_f32_e64 v64, s98, v228
	v_mul_f32_e64 v138, s52, v228
	v_mul_f32_e64 v65, s99, v228
	v_mul_f32_e64 v139, s53, v228
	v_pk_mul_f32 v[66:67], v[66:67], v[228:229]
	v_pk_mul_f32 v[140:141], v[140:141], v[228:229]
	v_exp_f32_e32 v64, v64
	v_exp_f32_e32 v138, v138
	v_exp_f32_e32 v65, v65
	v_exp_f32_e32 v139, v139
	v_exp_f32_e32 v66, v66
	v_exp_f32_e32 v140, v140
	v_exp_f32_e32 v67, v67
	v_exp_f32_e32 v141, v141
	v_lshlrev_b32_e32 v70, 16, v24
	v_lshlrev_b32_e32 v144, 16, v25
	v_and_b32_e32 v71, 0xffff0000, v24
	v_and_b32_e32 v145, 0xffff0000, v25
	v_pk_mul_f32 v[66:67], v[66:67], v[70:71]
	v_pk_mul_f32 v[140:141], v[140:141], v[144:145]
	v_cvt_pk_bf16_f32 v70, v66, v67
	v_cvt_pk_bf16_f32 v144, v140, v141
	ds_write_b16 v172, v70 offset:0
	ds_write_b16_d16_hi v172, v70 offset:128
	ds_write_b16 v172, v144 offset:2048
	ds_write_b16_d16_hi v172, v144 offset:2176
	s_and_saveexec_b64 s[20:21], vcc
	ds_write_b64 v163, v[64:65] offset:8192
	ds_write_b64 v163, v[138:139] offset:8256
	s_mov_b64 exec, s[20:21]
	s_waitcnt vmcnt(28)
	ds_write_b64 v28, v[152:153] offset:10240
	ds_write_b32 v30, v158 offset:4160
	ds_write_b64 v28, v[166:167] offset:15360
	ds_write_b32 v30, v159 offset:6240
	s_waitcnt lgkmcnt(0)
	s_barrier
	ds_read_b128 v[8:11], v29 offset:10240
	ds_read_b128 v[12:15], v29 offset:10256
	ds_read_b128 v[16:19], v29 offset:10272
	ds_read_b128 v[20:23], v29 offset:10288
	ds_read_b32 v24, v31 offset:4160
	ds_read_b128 v[32:35], v29 offset:15360
	ds_read_b128 v[36:39], v29 offset:15376
	ds_read_b128 v[40:43], v29 offset:15392
	ds_read_b128 v[44:47], v29 offset:15408
	ds_read_b32 v25, v31 offset:6240
	global_load_dwordx2 v[152:153], v230, s[26:27]
	global_load_dword v158, v231, s[58:59]
	s_add_u32 s26, s26, 0x1000
	s_addc_u32 s27, s27, 0
	s_add_u32 s58, s58, 0x10000
	s_addc_u32 s59, s59, 0
	global_load_dwordx2 v[166:167], v230, s[26:27]
	global_load_dword v159, v231, s[58:59]
	s_add_u32 s26, s26, 0x1000
	s_addc_u32 s27, s27, 0
	s_add_u32 s58, s58, 0x10000
	s_addc_u32 s59, s59, 0
	global_load_dwordx4 v[48:51], v232, s[34:35]
	global_load_dwordx4 v[52:55], v233, s[34:35]
	global_load_dwordx4 v[56:59], v232, s[34:35] offset:1024
	global_load_dwordx4 v[60:63], v233, s[34:35] offset:1024
	s_add_u32 s34, s34, 0x8000
	s_addc_u32 s35, s35, 0
	global_load_dwordx4 v[122:125], v232, s[34:35]
	global_load_dwordx4 v[126:129], v233, s[34:35]
	global_load_dwordx4 v[130:133], v232, s[34:35] offset:1024
	global_load_dwordx4 v[134:137], v233, s[34:35] offset:1024
	s_add_u32 s34, s34, 0x8000
	s_addc_u32 s35, s35, 0
	ds_read_b128 v[154:157], v75 offset:0
	ds_read_b128 v[240:243], v164 offset:8192
	ds_read_b128 v[236:239], v75 offset:64
	s_waitcnt lgkmcnt(3)
; DI float bf2f(unsigned x) { return __uint_as_float(x << 16); }
;     ...
;         auto ldchunk = [&](int n) {
;             const int tok = b * 4096 + n * 64 + l;
; #pragma unroll
;             for (int q = 0; q < 4; ++q) a4n[q] = *(const f32x4*)(GA + (size_t)tok * 16 + 4 * q);
;             krawn = *(const unsigned*)(GK + (size_t)tok * 512 + kc0);
; #pragma unroll
;             for (int e = 0; e < 2; ++e)
; #pragma unroll
;                 for (int ks = 0; ks < 2; ++ks)
;                     vfrn[e][ks] = *(const bf16x8*)(GVT + ((size_t)(b * 1024 + hh * 256 + (2 * w + e) * 16 + (l & 15))) * 4096 + n * 64 + ks * 32 + (l >> 4) * 8);
;         };
;         ldchunk(0);
;         for (int n = 0; n < 64; ++n) {
;             const int buf = n & 1;
;             f32x4 a4[4]; bf16x8 vfr[2][2];
; #pragma unroll
;             for (int q = 0; q < 4; ++q) a4[q] = a4n[q];
;             const unsigned kraw = krawn;
; #pragma unroll
;             for (int e = 0; e < 2; ++e)
; #pragma unroll
;                 for (int ks = 0; ks < 2; ++ks) vfr[e][ks] = vfrn[e][ks];
;             if (n + 1 < 64) ldchunk(n + 1);
;             float cum[2];
; #pragma unroll
;             for (int e = 0; e < 2; ++e) {
;                 float z = bb[e];
; #pragma unroll
;                 for (int q = 0; q < 4; ++q) { z += a4[q].x * wa[e][4 * q] + a4[q].y * wa[e][4 * q + 1] + a4[q].z * wa[e][4 * q + 2] + a4[q].w * wa[e][4 * q + 3]; }
;                 cum[e] = (fminf(z, 0.f) - __logf(1.f + __expf(-fabsf(z)))) * (1.f / 16.f);
;             }
; #pragma unroll
;             for (int o = 1; o < 64; o <<= 1) {
;                 const float t0 = __shfl_up(cum[0], o), t1 = __shfl_up(cum[1], o);
;                 if (l >= o) { cum[0] += t0; cum[1] += t1; }
;             }
;             const float tot0 = __shfl(cum[0], 63), tot1 = __shfl(cum[1], 63);
;             kdl[(buf * 16 + 2 * w) * 64 + l] = f2bf(bf2f(kraw & 0xffffu) * __expf(tot0 - cum[0]));
;             kdl[(buf * 16 + 2 * w + 1) * 64 + l] = f2bf(bf2f(kraw >> 16) * __expf(tot1 - cum[1]));
;             if (l == 0) { decl[buf * 16 + 2 * w] = __expf(tot0); decl[buf * 16 + 2 * w + 1] = __expf(tot1); }
;             __syncthreads();
;             const f32x4 d4 = *(const f32x4*)(decl + buf * 16 + (l >> 4) * 4);
; #pragma unroll
;             for (int e = 0; e < 2; ++e) acc[e] = acc[e] * d4;
; #pragma unroll
;             for (int ks = 0; ks < 2; ++ks) {
	v_pk_fma_f32 v[64:65], v[8:9], v[86:87], v[118:119] op_sel:[0,0,0] op_sel_hi:[0,1,1]
	v_pk_fma_f32 v[138:139], v[32:33], v[86:87], v[118:119] op_sel:[0,0,0] op_sel_hi:[0,1,1]
	v_pk_mul_f32 v[66:67], v[16:17], v[102:103] op_sel:[0,0] op_sel_hi:[0,1]
	v_pk_mul_f32 v[140:141], v[40:41], v[102:103] op_sel:[0,0] op_sel_hi:[0,1]
	v_pk_fma_f32 v[64:65], v[8:9], v[88:89], v[64:65] op_sel:[1,0,0] op_sel_hi:[1,1,1]
	v_pk_fma_f32 v[138:139], v[32:33], v[88:89], v[138:139] op_sel:[1,0,0] op_sel_hi:[1,1,1]
	v_pk_fma_f32 v[66:67], v[16:17], v[104:105], v[66:67] op_sel:[1,0,0] op_sel_hi:[1,1,1]
	v_pk_fma_f32 v[140:141], v[40:41], v[104:105], v[140:141] op_sel:[1,0,0] op_sel_hi:[1,1,1]
	v_pk_fma_f32 v[64:65], v[10:11], v[90:91], v[64:65] op_sel:[0,0,0] op_sel_hi:[0,1,1]
	v_pk_fma_f32 v[138:139], v[34:35], v[90:91], v[138:139] op_sel:[0,0,0] op_sel_hi:[0,1,1]
	v_pk_fma_f32 v[66:67], v[18:19], v[106:107], v[66:67] op_sel:[0,0,0] op_sel_hi:[0,1,1]
	v_pk_fma_f32 v[140:141], v[42:43], v[106:107], v[140:141] op_sel:[0,0,0] op_sel_hi:[0,1,1]
	v_pk_fma_f32 v[64:65], v[10:11], v[92:93], v[64:65] op_sel:[1,0,0] op_sel_hi:[1,1,1]
	v_pk_fma_f32 v[138:139], v[34:35], v[92:93], v[138:139] op_sel:[1,0,0] op_sel_hi:[1,1,1]
	v_pk_fma_f32 v[66:67], v[18:19], v[108:109], v[66:67] op_sel:[1,0,0] op_sel_hi:[1,1,1]
	v_pk_fma_f32 v[140:141], v[42:43], v[108:109], v[140:141] op_sel:[1,0,0] op_sel_hi:[1,1,1]
	v_pk_fma_f32 v[64:65], v[12:13], v[94:95], v[64:65] op_sel:[0,0,0] op_sel_hi:[0,1,1]
	v_pk_fma_f32 v[138:139], v[36:37], v[94:95], v[138:139] op_sel:[0,0,0] op_sel_hi:[0,1,1]
	v_pk_fma_f32 v[66:67], v[20:21], v[110:111], v[66:67] op_sel:[0,0,0] op_sel_hi:[0,1,1]
	v_pk_fma_f32 v[140:141], v[44:45], v[110:111], v[140:141] op_sel:[0,0,0] op_sel_hi:[0,1,1]
	v_pk_fma_f32 v[64:65], v[12:13], v[96:97], v[64:65] op_sel:[1,0,0] op_sel_hi:[1,1,1]
	v_pk_fma_f32 v[138:139], v[36:37], v[96:97], v[138:139] op_sel:[1,0,0] op_sel_hi:[1,1,1]
	v_pk_fma_f32 v[66:67], v[20:21], v[112:113], v[66:67] op_sel:[1,0,0] op_sel_hi:[1,1,1]
	v_pk_fma_f32 v[140:141], v[44:45], v[112:113], v[140:141] op_sel:[1,0,0] op_sel_hi:[1,1,1]
	v_pk_fma_f32 v[64:65], v[14:15], v[98:99], v[64:65] op_sel:[0,0,0] op_sel_hi:[0,1,1]
	v_pk_fma_f32 v[138:139], v[38:39], v[98:99], v[138:139] op_sel:[0,0,0] op_sel_hi:[0,1,1]
	v_pk_fma_f32 v[66:67], v[22:23], v[114:115], v[66:67] op_sel:[0,0,0] op_sel_hi:[0,1,1]
	v_pk_fma_f32 v[140:141], v[46:47], v[114:115], v[140:141] op_sel:[0,0,0] op_sel_hi:[0,1,1]
	v_pk_fma_f32 v[64:65], v[14:15], v[100:101], v[64:65] op_sel:[1,0,0] op_sel_hi:[1,1,1]
	v_pk_fma_f32 v[138:139], v[38:39], v[100:101], v[138:139] op_sel:[1,0,0] op_sel_hi:[1,1,1]
	v_pk_fma_f32 v[66:67], v[22:23], v[116:117], v[66:67] op_sel:[1,0,0] op_sel_hi:[1,1,1]
	v_pk_fma_f32 v[140:141], v[46:47], v[116:117], v[140:141] op_sel:[1,0,0] op_sel_hi:[1,1,1]
	v_pk_add_f32 v[64:65], v[64:65], v[66:67]
	v_pk_add_f32 v[138:139], v[138:139], v[140:141]
	s_waitcnt lgkmcnt(0)
	v_pk_mul_f32 v[0:1], v[0:1], v[240:241]
	v_pk_mul_f32 v[2:3], v[2:3], v[242:243]
	v_pk_mul_f32 v[4:5], v[4:5], v[240:241]
	v_pk_mul_f32 v[6:7], v[6:7], v[242:243]
	s_waitcnt vmcnt(12)
	s_nop 0
	v_mfma_f32_16x16x32_bf16 v[0:3], v[154:157], v[178:181], v[0:3]
	v_mfma_f32_16x16x32_bf16 v[4:7], v[154:157], v[186:189], v[4:7]
	v_mfma_f32_16x16x32_bf16 v[0:3], v[236:239], v[182:185], v[0:3]
	v_mfma_f32_16x16x32_bf16 v[4:7], v[236:239], v[190:193], v[4:7]
	ds_read_b128 v[154:157], v75 offset:2048
	ds_read_b128 v[240:243], v164 offset:8256
	ds_read_b128 v[236:239], v75 offset:2112
	v_mul_f32_e64 v66, |v64|, v220
	v_mul_f32_e64 v140, |v138|, v220
	v_mul_f32_e64 v67, |v65|, v220
	v_mul_f32_e64 v141, |v139|, v220
	v_exp_f32_e32 v66, v66
	v_exp_f32_e32 v140, v140
	v_exp_f32_e32 v67, v67
	v_exp_f32_e32 v141, v141
	v_min_f32_e32 v68, 0, v64
	v_min_f32_e32 v142, 0, v138
	v_min_f32_e32 v69, 0, v65
	v_min_f32_e32 v143, 0, v139
	v_pk_add_f32 v[66:67], v[66:67], v[222:223]
	v_pk_add_f32 v[140:141], v[140:141], v[222:223]
	v_log_f32_e32 v64, v66
	v_log_f32_e32 v138, v140
	v_log_f32_e32 v65, v67
	v_log_f32_e32 v139, v141
	v_pk_mul_f32 v[66:67], v[64:65], v[224:225]
	v_pk_mul_f32 v[140:141], v[138:139], v[224:225]
	v_pk_fma_f32 v[70:71], v[64:65], v[224:225], v[66:67] neg_lo:[0,0,1] neg_hi:[0,0,1]
	v_pk_fma_f32 v[144:145], v[138:139], v[224:225], v[140:141] neg_lo:[0,0,1] neg_hi:[0,0,1]
	v_pk_fma_f32 v[70:71], v[64:65], v[226:227], v[70:71]
	v_pk_fma_f32 v[144:145], v[138:139], v[226:227], v[144:145]
	v_pk_fma_f32 v[70:71], v[64:65], v[224:225], v[70:71]
	v_pk_fma_f32 v[144:145], v[138:139], v[224:225], v[144:145]
	v_pk_add_f32 v[68:69], v[68:69], v[70:71] neg_lo:[0,1] neg_hi:[0,1]
	v_pk_add_f32 v[142:143], v[142:143], v[144:145] neg_lo:[0,1] neg_hi:[0,1]
	v_pk_mul_f32 v[68:69], v[68:69], v[214:215]
	v_pk_mul_f32 v[142:143], v[142:143], v[214:215]
	v_cvt_pk_bf16_f32 v244, v0, v1
	v_cvt_pk_bf16_f32 v245, v2, v3
	v_cvt_pk_bf16_f32 v246, v4, v5
	v_cvt_pk_bf16_f32 v247, v6, v7
	global_store_dwordx2 v234, v[244:245], s[100:101]
	global_store_dwordx2 v235, v[246:247], s[100:101]
	s_add_u32 s100, s100, 0x40000
	s_addc_u32 s101, s101, 0
	s_waitcnt lgkmcnt(0)
	v_pk_mul_f32 v[0:1], v[0:1], v[240:241]
	v_pk_mul_f32 v[2:3], v[2:3], v[242:243]
	v_pk_mul_f32 v[4:5], v[4:5], v[240:241]
	v_pk_mul_f32 v[6:7], v[6:7], v[242:243]
	s_waitcnt vmcnt(14)
; DI float bf2f(unsigned x) { return __uint_as_float(x << 16); }
;     ...
;         auto ldchunk = [&](int n) {
;             const int tok = b * 4096 + n * 64 + l;
; #pragma unroll
;             for (int q = 0; q < 4; ++q) a4n[q] = *(const f32x4*)(GA + (size_t)tok * 16 + 4 * q);
;             krawn = *(const unsigned*)(GK + (size_t)tok * 512 + kc0);
; #pragma unroll
;             for (int e = 0; e < 2; ++e)
; #pragma unroll
;                 for (int ks = 0; ks < 2; ++ks)
;                     vfrn[e][ks] = *(const bf16x8*)(GVT + ((size_t)(b * 1024 + hh * 256 + (2 * w + e) * 16 + (l & 15))) * 4096 + n * 64 + ks * 32 + (l >> 4) * 8);
;         };
;         ldchunk(0);
;         for (int n = 0; n < 64; ++n) {
;             const int buf = n & 1;
;             f32x4 a4[4]; bf16x8 vfr[2][2];
; #pragma unroll
;             for (int q = 0; q < 4; ++q) a4[q] = a4n[q];
;             const unsigned kraw = krawn;
; #pragma unroll
;             for (int e = 0; e < 2; ++e)
; #pragma unroll
;                 for (int ks = 0; ks < 2; ++ks) vfr[e][ks] = vfrn[e][ks];
;             if (n + 1 < 64) ldchunk(n + 1);
;             float cum[2];
; #pragma unroll
;             for (int e = 0; e < 2; ++e) {
;                 float z = bb[e];
; #pragma unroll
;                 for (int q = 0; q < 4; ++q) { z += a4[q].x * wa[e][4 * q] + a4[q].y * wa[e][4 * q + 1] + a4[q].z * wa[e][4 * q + 2] + a4[q].w * wa[e][4 * q + 3]; }
;                 cum[e] = (fminf(z, 0.f) - __logf(1.f + __expf(-fabsf(z)))) * (1.f / 16.f);
;             }
; #pragma unroll
;             for (int o = 1; o < 64; o <<= 1) {
;                 const float t0 = __shfl_up(cum[0], o), t1 = __shfl_up(cum[1], o);
;                 if (l >= o) { cum[0] += t0; cum[1] += t1; }
;             }
;             const float tot0 = __shfl(cum[0], 63), tot1 = __shfl(cum[1], 63);
;             kdl[(buf * 16 + 2 * w) * 64 + l] = f2bf(bf2f(kraw & 0xffffu) * __expf(tot0 - cum[0]));
;             kdl[(buf * 16 + 2 * w + 1) * 64 + l] = f2bf(bf2f(kraw >> 16) * __expf(tot1 - cum[1]));
;             if (l == 0) { decl[buf * 16 + 2 * w] = __expf(tot0); decl[buf * 16 + 2 * w + 1] = __expf(tot1); }
;             __syncthreads();
;             const f32x4 d4 = *(const f32x4*)(decl + buf * 16 + (l >> 4) * 4);
; #pragma unroll
;             for (int e = 0; e < 2; ++e) acc[e] = acc[e] * d4;
; #pragma unroll
;             for (int ks = 0; ks < 2; ++ks) {
	s_nop 0
	v_mfma_f32_16x16x32_bf16 v[0:3], v[154:157], v[194:197], v[0:3]
	v_mfma_f32_16x16x32_bf16 v[4:7], v[154:157], v[202:205], v[4:7]
	v_mfma_f32_16x16x32_bf16 v[0:3], v[236:239], v[198:201], v[0:3]
	v_mfma_f32_16x16x32_bf16 v[4:7], v[236:239], v[206:209], v[4:7]
	v_add_f32_dpp v68, v68, v68 row_shr:1 row_mask:0xf bank_mask:0xf
	v_add_f32_dpp v142, v142, v142 row_shr:1 row_mask:0xf bank_mask:0xf
	v_add_f32_dpp v69, v69, v69 row_shr:1 row_mask:0xf bank_mask:0xf
	v_add_f32_dpp v143, v143, v143 row_shr:1 row_mask:0xf bank_mask:0xf
	v_add_f32_dpp v68, v68, v68 row_shr:2 row_mask:0xf bank_mask:0xf
	v_add_f32_dpp v142, v142, v142 row_shr:2 row_mask:0xf bank_mask:0xf
	v_add_f32_dpp v69, v69, v69 row_shr:2 row_mask:0xf bank_mask:0xf
	v_add_f32_dpp v143, v143, v143 row_shr:2 row_mask:0xf bank_mask:0xf
	v_add_f32_dpp v68, v68, v68 row_shr:4 row_mask:0xf bank_mask:0xf
	v_add_f32_dpp v142, v142, v142 row_shr:4 row_mask:0xf bank_mask:0xf
	v_add_f32_dpp v69, v69, v69 row_shr:4 row_mask:0xf bank_mask:0xf
	v_add_f32_dpp v143, v143, v143 row_shr:4 row_mask:0xf bank_mask:0xf
	v_add_f32_dpp v68, v68, v68 row_shr:8 row_mask:0xf bank_mask:0xf
	v_add_f32_dpp v142, v142, v142 row_shr:8 row_mask:0xf bank_mask:0xf
	v_add_f32_dpp v69, v69, v69 row_shr:8 row_mask:0xf bank_mask:0xf
	v_add_f32_dpp v143, v143, v143 row_shr:8 row_mask:0xf bank_mask:0xf
	v_add_f32_dpp v68, v68, v68 row_bcast:15 row_mask:0xa bank_mask:0xf
	v_add_f32_dpp v142, v142, v142 row_bcast:15 row_mask:0xa bank_mask:0xf
	v_add_f32_dpp v69, v69, v69 row_bcast:15 row_mask:0xa bank_mask:0xf
	v_add_f32_dpp v143, v143, v143 row_bcast:15 row_mask:0xa bank_mask:0xf
	v_add_f32_dpp v68, v68, v68 row_bcast:31 row_mask:0xc bank_mask:0xf
	v_add_f32_dpp v142, v142, v142 row_bcast:31 row_mask:0xc bank_mask:0xf
	v_add_f32_dpp v69, v69, v69 row_bcast:31 row_mask:0xc bank_mask:0xf
	v_add_f32_dpp v143, v143, v143 row_bcast:31 row_mask:0xc bank_mask:0xf
	v_readlane_b32 s98, v68, 63
	v_readlane_b32 s52, v142, 63
	v_readlane_b32 s99, v69, 63
	v_readlane_b32 s53, v143, 63
	s_nop 0
	v_pk_add_f32 v[66:67], s[98:99], v[68:69] neg_lo:[0,1] neg_hi:[0,1]
	v_pk_add_f32 v[140:141], s[52:53], v[142:143] neg_lo:[0,1] neg_hi:[0,1]
	v_mul_f32_e64 v64, s98, v228
	v_mul_f32_e64 v138, s52, v228
	v_mul_f32_e64 v65, s99, v228
	v_mul_f32_e64 v139, s53, v228
	v_pk_mul_f32 v[66:67], v[66:67], v[228:229]
	v_pk_mul_f32 v[140:141], v[140:141], v[228:229]
	v_exp_f32_e32 v64, v64
	v_exp_f32_e32 v138, v138
	v_exp_f32_e32 v65, v65
	v_exp_f32_e32 v139, v139
	v_exp_f32_e32 v66, v66
	v_exp_f32_e32 v140, v140
	v_exp_f32_e32 v67, v67
	v_exp_f32_e32 v141, v141
	v_lshlrev_b32_e32 v70, 16, v24
	v_lshlrev_b32_e32 v144, 16, v25
	v_and_b32_e32 v71, 0xffff0000, v24
	v_and_b32_e32 v145, 0xffff0000, v25
	v_pk_mul_f32 v[66:67], v[66:67], v[70:71]
	v_pk_mul_f32 v[140:141], v[140:141], v[144:145]
	v_cvt_pk_bf16_f32 v70, v66, v67
	v_cvt_pk_bf16_f32 v144, v140, v141
	v_cvt_pk_bf16_f32 v244, v0, v1
	v_cvt_pk_bf16_f32 v245, v2, v3
	v_cvt_pk_bf16_f32 v246, v4, v5
	v_cvt_pk_bf16_f32 v247, v6, v7
	global_store_dwordx2 v234, v[244:245], s[100:101]
	global_store_dwordx2 v235, v[246:247], s[100:101]
	s_add_u32 s100, s100, 0x40000
	s_addc_u32 s101, s101, 0
	ds_write_b16 v172, v70 offset:4096
	ds_write_b16_d16_hi v172, v70 offset:4224
	ds_write_b16 v172, v144 offset:6144
	ds_write_b16_d16_hi v172, v144 offset:6272
	s_and_saveexec_b64 s[20:21], vcc
	ds_write_b64 v163, v[64:65] offset:8320
	ds_write_b64 v163, v[138:139] offset:8384
	s_mov_b64 exec, s[20:21]
	s_waitcnt vmcnt(24)
	ds_write_b64 v28, v[146:147] offset:0
	ds_write_b32 v30, v150 offset:0
	ds_write_b64 v28, v[148:149] offset:5120
	ds_write_b32 v30, v151 offset:2080
	s_waitcnt lgkmcnt(0)
	s_barrier
	ds_read_b128 v[8:11], v29 offset:0
	ds_read_b128 v[12:15], v29 offset:16
	ds_read_b128 v[16:19], v29 offset:32
	ds_read_b128 v[20:23], v29 offset:48
	ds_read_b32 v24, v31 offset:0
	ds_read_b128 v[32:35], v29 offset:5120
	ds_read_b128 v[36:39], v29 offset:5136
	ds_read_b128 v[40:43], v29 offset:5152
	ds_read_b128 v[44:47], v29 offset:5168
	ds_read_b32 v25, v31 offset:2080
	global_load_dwordx2 v[146:147], v230, s[26:27]
	global_load_dword v150, v231, s[58:59]
	s_add_u32 s26, s26, 0x1000
	s_addc_u32 s27, s27, 0
	s_add_u32 s58, s58, 0x10000
	s_addc_u32 s59, s59, 0
	global_load_dwordx2 v[148:149], v230, s[26:27]
	global_load_dword v151, v231, s[58:59]
	s_add_u32 s26, s26, 0x1000
	s_addc_u32 s27, s27, 0
	s_add_u32 s58, s58, 0x10000
	s_addc_u32 s59, s59, 0
	global_load_dwordx4 v[178:181], v232, s[34:35]
	global_load_dwordx4 v[182:185], v233, s[34:35]
	global_load_dwordx4 v[186:189], v232, s[34:35] offset:1024
	global_load_dwordx4 v[190:193], v233, s[34:35] offset:1024
	s_add_u32 s34, s34, 0x8000
	s_addc_u32 s35, s35, 0
	global_load_dwordx4 v[194:197], v232, s[34:35]
	global_load_dwordx4 v[198:201], v233, s[34:35]
	global_load_dwordx4 v[202:205], v232, s[34:35] offset:1024
	global_load_dwordx4 v[206:209], v233, s[34:35] offset:1024
	s_add_u32 s34, s34, 0x8000
	s_addc_u32 s35, s35, 0
	ds_read_b128 v[154:157], v75 offset:4096
	ds_read_b128 v[240:243], v164 offset:8320
	ds_read_b128 v[236:239], v75 offset:4160
	s_waitcnt lgkmcnt(3)
; DI float bf2f(unsigned x) { return __uint_as_float(x << 16); }
;     ...
;         auto ldchunk = [&](int n) {
;             const int tok = b * 4096 + n * 64 + l;
; #pragma unroll
;             for (int q = 0; q < 4; ++q) a4n[q] = *(const f32x4*)(GA + (size_t)tok * 16 + 4 * q);
;             krawn = *(const unsigned*)(GK + (size_t)tok * 512 + kc0);
; #pragma unroll
;             for (int e = 0; e < 2; ++e)
; #pragma unroll
;                 for (int ks = 0; ks < 2; ++ks)
;                     vfrn[e][ks] = *(const bf16x8*)(GVT + ((size_t)(b * 1024 + hh * 256 + (2 * w + e) * 16 + (l & 15))) * 4096 + n * 64 + ks * 32 + (l >> 4) * 8);
;         };
;         ldchunk(0);
;         for (int n = 0; n < 64; ++n) {
;             const int buf = n & 1;
;             f32x4 a4[4]; bf16x8 vfr[2][2];
; #pragma unroll
;             for (int q = 0; q < 4; ++q) a4[q] = a4n[q];
;             const unsigned kraw = krawn;
; #pragma unroll
;             for (int e = 0; e < 2; ++e)
; #pragma unroll
;                 for (int ks = 0; ks < 2; ++ks) vfr[e][ks] = vfrn[e][ks];
;             if (n + 1 < 64) ldchunk(n + 1);
;             float cum[2];
; #pragma unroll
;             for (int e = 0; e < 2; ++e) {
;                 float z = bb[e];
; #pragma unroll
;                 for (int q = 0; q < 4; ++q) { z += a4[q].x * wa[e][4 * q] + a4[q].y * wa[e][4 * q + 1] + a4[q].z * wa[e][4 * q + 2] + a4[q].w * wa[e][4 * q + 3]; }
;                 cum[e] = (fminf(z, 0.f) - __logf(1.f + __expf(-fabsf(z)))) * (1.f / 16.f);
;             }
; #pragma unroll
;             for (int o = 1; o < 64; o <<= 1) {
;                 const float t0 = __shfl_up(cum[0], o), t1 = __shfl_up(cum[1], o);
;                 if (l >= o) { cum[0] += t0; cum[1] += t1; }
;             }
;             const float tot0 = __shfl(cum[0], 63), tot1 = __shfl(cum[1], 63);
;             kdl[(buf * 16 + 2 * w) * 64 + l] = f2bf(bf2f(kraw & 0xffffu) * __expf(tot0 - cum[0]));
;             kdl[(buf * 16 + 2 * w + 1) * 64 + l] = f2bf(bf2f(kraw >> 16) * __expf(tot1 - cum[1]));
;             if (l == 0) { decl[buf * 16 + 2 * w] = __expf(tot0); decl[buf * 16 + 2 * w + 1] = __expf(tot1); }
;             __syncthreads();
;             const f32x4 d4 = *(const f32x4*)(decl + buf * 16 + (l >> 4) * 4);
; #pragma unroll
;             for (int e = 0; e < 2; ++e) acc[e] = acc[e] * d4;
; #pragma unroll
;             for (int ks = 0; ks < 2; ++ks) {
	v_pk_fma_f32 v[64:65], v[8:9], v[86:87], v[118:119] op_sel:[0,0,0] op_sel_hi:[0,1,1]
	v_pk_fma_f32 v[138:139], v[32:33], v[86:87], v[118:119] op_sel:[0,0,0] op_sel_hi:[0,1,1]
	v_pk_mul_f32 v[66:67], v[16:17], v[102:103] op_sel:[0,0] op_sel_hi:[0,1]
	v_pk_mul_f32 v[140:141], v[40:41], v[102:103] op_sel:[0,0] op_sel_hi:[0,1]
	v_pk_fma_f32 v[64:65], v[8:9], v[88:89], v[64:65] op_sel:[1,0,0] op_sel_hi:[1,1,1]
	v_pk_fma_f32 v[138:139], v[32:33], v[88:89], v[138:139] op_sel:[1,0,0] op_sel_hi:[1,1,1]
	v_pk_fma_f32 v[66:67], v[16:17], v[104:105], v[66:67] op_sel:[1,0,0] op_sel_hi:[1,1,1]
	v_pk_fma_f32 v[140:141], v[40:41], v[104:105], v[140:141] op_sel:[1,0,0] op_sel_hi:[1,1,1]
	v_pk_fma_f32 v[64:65], v[10:11], v[90:91], v[64:65] op_sel:[0,0,0] op_sel_hi:[0,1,1]
	v_pk_fma_f32 v[138:139], v[34:35], v[90:91], v[138:139] op_sel:[0,0,0] op_sel_hi:[0,1,1]
	v_pk_fma_f32 v[66:67], v[18:19], v[106:107], v[66:67] op_sel:[0,0,0] op_sel_hi:[0,1,1]
	v_pk_fma_f32 v[140:141], v[42:43], v[106:107], v[140:141] op_sel:[0,0,0] op_sel_hi:[0,1,1]
	v_pk_fma_f32 v[64:65], v[10:11], v[92:93], v[64:65] op_sel:[1,0,0] op_sel_hi:[1,1,1]
	v_pk_fma_f32 v[138:139], v[34:35], v[92:93], v[138:139] op_sel:[1,0,0] op_sel_hi:[1,1,1]
	v_pk_fma_f32 v[66:67], v[18:19], v[108:109], v[66:67] op_sel:[1,0,0] op_sel_hi:[1,1,1]
	v_pk_fma_f32 v[140:141], v[42:43], v[108:109], v[140:141] op_sel:[1,0,0] op_sel_hi:[1,1,1]
	v_pk_fma_f32 v[64:65], v[12:13], v[94:95], v[64:65] op_sel:[0,0,0] op_sel_hi:[0,1,1]
	v_pk_fma_f32 v[138:139], v[36:37], v[94:95], v[138:139] op_sel:[0,0,0] op_sel_hi:[0,1,1]
	v_pk_fma_f32 v[66:67], v[20:21], v[110:111], v[66:67] op_sel:[0,0,0] op_sel_hi:[0,1,1]
	v_pk_fma_f32 v[140:141], v[44:45], v[110:111], v[140:141] op_sel:[0,0,0] op_sel_hi:[0,1,1]
	v_pk_fma_f32 v[64:65], v[12:13], v[96:97], v[64:65] op_sel:[1,0,0] op_sel_hi:[1,1,1]
	v_pk_fma_f32 v[138:139], v[36:37], v[96:97], v[138:139] op_sel:[1,0,0] op_sel_hi:[1,1,1]
	v_pk_fma_f32 v[66:67], v[20:21], v[112:113], v[66:67] op_sel:[1,0,0] op_sel_hi:[1,1,1]
	v_pk_fma_f32 v[140:141], v[44:45], v[112:113], v[140:141] op_sel:[1,0,0] op_sel_hi:[1,1,1]
	v_pk_fma_f32 v[64:65], v[14:15], v[98:99], v[64:65] op_sel:[0,0,0] op_sel_hi:[0,1,1]
	v_pk_fma_f32 v[138:139], v[38:39], v[98:99], v[138:139] op_sel:[0,0,0] op_sel_hi:[0,1,1]
	v_pk_fma_f32 v[66:67], v[22:23], v[114:115], v[66:67] op_sel:[0,0,0] op_sel_hi:[0,1,1]
	v_pk_fma_f32 v[140:141], v[46:47], v[114:115], v[140:141] op_sel:[0,0,0] op_sel_hi:[0,1,1]
	v_pk_fma_f32 v[64:65], v[14:15], v[100:101], v[64:65] op_sel:[1,0,0] op_sel_hi:[1,1,1]
	v_pk_fma_f32 v[138:139], v[38:39], v[100:101], v[138:139] op_sel:[1,0,0] op_sel_hi:[1,1,1]
	v_pk_fma_f32 v[66:67], v[22:23], v[116:117], v[66:67] op_sel:[1,0,0] op_sel_hi:[1,1,1]
	v_pk_fma_f32 v[140:141], v[46:47], v[116:117], v[140:141] op_sel:[1,0,0] op_sel_hi:[1,1,1]
	v_pk_add_f32 v[64:65], v[64:65], v[66:67]
	v_pk_add_f32 v[138:139], v[138:139], v[140:141]
	s_waitcnt lgkmcnt(0)
	v_pk_mul_f32 v[0:1], v[0:1], v[240:241]
	v_pk_mul_f32 v[2:3], v[2:3], v[242:243]
	v_pk_mul_f32 v[4:5], v[4:5], v[240:241]
	v_pk_mul_f32 v[6:7], v[6:7], v[242:243]
	s_waitcnt vmcnt(16)
	s_nop 0
	v_mfma_f32_16x16x32_bf16 v[0:3], v[154:157], v[48:51], v[0:3]
	v_mfma_f32_16x16x32_bf16 v[4:7], v[154:157], v[56:59], v[4:7]
	v_mfma_f32_16x16x32_bf16 v[0:3], v[236:239], v[52:55], v[0:3]
	v_mfma_f32_16x16x32_bf16 v[4:7], v[236:239], v[60:63], v[4:7]
	ds_read_b128 v[154:157], v75 offset:6144
	ds_read_b128 v[240:243], v164 offset:8384
	ds_read_b128 v[236:239], v75 offset:6208
	v_mul_f32_e64 v66, |v64|, v220
	v_mul_f32_e64 v140, |v138|, v220
	v_mul_f32_e64 v67, |v65|, v220
	v_mul_f32_e64 v141, |v139|, v220
	v_exp_f32_e32 v66, v66
	v_exp_f32_e32 v140, v140
	v_exp_f32_e32 v67, v67
	v_exp_f32_e32 v141, v141
	v_min_f32_e32 v68, 0, v64
	v_min_f32_e32 v142, 0, v138
	v_min_f32_e32 v69, 0, v65
	v_min_f32_e32 v143, 0, v139
	v_pk_add_f32 v[66:67], v[66:67], v[222:223]
	v_pk_add_f32 v[140:141], v[140:141], v[222:223]
	v_log_f32_e32 v64, v66
	v_log_f32_e32 v138, v140
	v_log_f32_e32 v65, v67
	v_log_f32_e32 v139, v141
	v_pk_mul_f32 v[66:67], v[64:65], v[224:225]
	v_pk_mul_f32 v[140:141], v[138:139], v[224:225]
	v_pk_fma_f32 v[70:71], v[64:65], v[224:225], v[66:67] neg_lo:[0,0,1] neg_hi:[0,0,1]
	v_pk_fma_f32 v[144:145], v[138:139], v[224:225], v[140:141] neg_lo:[0,0,1] neg_hi:[0,0,1]
	v_pk_fma_f32 v[70:71], v[64:65], v[226:227], v[70:71]
	v_pk_fma_f32 v[144:145], v[138:139], v[226:227], v[144:145]
	v_pk_fma_f32 v[70:71], v[64:65], v[224:225], v[70:71]
	v_pk_fma_f32 v[144:145], v[138:139], v[224:225], v[144:145]
	v_pk_add_f32 v[68:69], v[68:69], v[70:71] neg_lo:[0,1] neg_hi:[0,1]
	v_pk_add_f32 v[142:143], v[142:143], v[144:145] neg_lo:[0,1] neg_hi:[0,1]
	v_pk_mul_f32 v[68:69], v[68:69], v[214:215]
	v_pk_mul_f32 v[142:143], v[142:143], v[214:215]
	v_cvt_pk_bf16_f32 v244, v0, v1
	v_cvt_pk_bf16_f32 v245, v2, v3
	v_cvt_pk_bf16_f32 v246, v4, v5
	v_cvt_pk_bf16_f32 v247, v6, v7
	global_store_dwordx2 v234, v[244:245], s[100:101]
	global_store_dwordx2 v235, v[246:247], s[100:101]
	s_add_u32 s100, s100, 0x40000
	s_addc_u32 s101, s101, 0
	s_waitcnt lgkmcnt(0)
	v_pk_mul_f32 v[0:1], v[0:1], v[240:241]
	v_pk_mul_f32 v[2:3], v[2:3], v[242:243]
	v_pk_mul_f32 v[4:5], v[4:5], v[240:241]
	v_pk_mul_f32 v[6:7], v[6:7], v[242:243]
	s_waitcnt vmcnt(18)
; #define MFMA16(a, b, c) __builtin_amdgcn_mfma_f32_16x16x32_bf16((a), (b), (c), 0, 0, 0)
; DI bf16_t f2bf(float x) { return (bf16_t)(pk2(x, 0.f) & 0xffffu); }
; DI float bf2f(unsigned x) { return __uint_as_float(x << 16); }
; DI u32x2 pk4(float a, float b, float c, float d) { u32x2 r; r.x = pk2(a, b); r.y = pk2(c, d); return r; }
;     ...
; #pragma unroll
;             for (int o = 1; o < 64; o <<= 1) {
;                 const float t0 = __shfl_up(cum[0], o), t1 = __shfl_up(cum[1], o);
;                 if (l >= o) { cum[0] += t0; cum[1] += t1; }
;             }
;             const float tot0 = __shfl(cum[0], 63), tot1 = __shfl(cum[1], 63);
;             kdl[(buf * 16 + 2 * w) * 64 + l] = f2bf(bf2f(kraw & 0xffffu) * __expf(tot0 - cum[0]));
;             kdl[(buf * 16 + 2 * w + 1) * 64 + l] = f2bf(bf2f(kraw >> 16) * __expf(tot1 - cum[1]));
;             if (l == 0) { decl[buf * 16 + 2 * w] = __expf(tot0); decl[buf * 16 + 2 * w + 1] = __expf(tot1); }
;             __syncthreads();
;             const f32x4 d4 = *(const f32x4*)(decl + buf * 16 + (l >> 4) * 4);
; #pragma unroll
;             for (int e = 0; e < 2; ++e) acc[e] = acc[e] * d4;
; #pragma unroll
;             for (int ks = 0; ks < 2; ++ks) {
;                 const bf16x8 af = *(const bf16x8*)(kdl + (buf * 16 + (l & 15)) * 64 + ks * 32 + (l >> 4) * 8);
; #pragma unroll
;                 for (int e = 0; e < 2; ++e) acc[e] = MFMA16(af, vfr[e][ks], acc[e]);
;             }
;             const int cidx = b * 64 + n;
; #pragma unroll
;             for (int e = 0; e < 2; ++e) {
;                 const int vv = (2 * w + e) * 16 + (l & 15);
;                 *(u32x2*)(ST + (((size_t)(cidx * 4 + hh)) * 256 + vv) * 128 + ksl * 16 + (l >> 4) * 4) = pk4(acc[e].x, acc[e].y, acc[e].z, acc[e].w);
;             }
	s_nop 0
	v_mfma_f32_16x16x32_bf16 v[0:3], v[154:157], v[122:125], v[0:3]
	v_mfma_f32_16x16x32_bf16 v[4:7], v[154:157], v[130:133], v[4:7]
	v_mfma_f32_16x16x32_bf16 v[0:3], v[236:239], v[126:129], v[0:3]
	v_mfma_f32_16x16x32_bf16 v[4:7], v[236:239], v[134:137], v[4:7]
	v_add_f32_dpp v68, v68, v68 row_shr:1 row_mask:0xf bank_mask:0xf
	v_add_f32_dpp v142, v142, v142 row_shr:1 row_mask:0xf bank_mask:0xf
	v_add_f32_dpp v69, v69, v69 row_shr:1 row_mask:0xf bank_mask:0xf
	v_add_f32_dpp v143, v143, v143 row_shr:1 row_mask:0xf bank_mask:0xf
	v_add_f32_dpp v68, v68, v68 row_shr:2 row_mask:0xf bank_mask:0xf
	v_add_f32_dpp v142, v142, v142 row_shr:2 row_mask:0xf bank_mask:0xf
	v_add_f32_dpp v69, v69, v69 row_shr:2 row_mask:0xf bank_mask:0xf
	v_add_f32_dpp v143, v143, v143 row_shr:2 row_mask:0xf bank_mask:0xf
	v_add_f32_dpp v68, v68, v68 row_shr:4 row_mask:0xf bank_mask:0xf
	v_add_f32_dpp v142, v142, v142 row_shr:4 row_mask:0xf bank_mask:0xf
	v_add_f32_dpp v69, v69, v69 row_shr:4 row_mask:0xf bank_mask:0xf
	v_add_f32_dpp v143, v143, v143 row_shr:4 row_mask:0xf bank_mask:0xf
	v_add_f32_dpp v68, v68, v68 row_shr:8 row_mask:0xf bank_mask:0xf
	v_add_f32_dpp v142, v142, v142 row_shr:8 row_mask:0xf bank_mask:0xf
	v_add_f32_dpp v69, v69, v69 row_shr:8 row_mask:0xf bank_mask:0xf
	v_add_f32_dpp v143, v143, v143 row_shr:8 row_mask:0xf bank_mask:0xf
	v_add_f32_dpp v68, v68, v68 row_bcast:15 row_mask:0xa bank_mask:0xf
	v_add_f32_dpp v142, v142, v142 row_bcast:15 row_mask:0xa bank_mask:0xf
	v_add_f32_dpp v69, v69, v69 row_bcast:15 row_mask:0xa bank_mask:0xf
	v_add_f32_dpp v143, v143, v143 row_bcast:15 row_mask:0xa bank_mask:0xf
	v_add_f32_dpp v68, v68, v68 row_bcast:31 row_mask:0xc bank_mask:0xf
	v_add_f32_dpp v142, v142, v142 row_bcast:31 row_mask:0xc bank_mask:0xf
	v_add_f32_dpp v69, v69, v69 row_bcast:31 row_mask:0xc bank_mask:0xf
	v_add_f32_dpp v143, v143, v143 row_bcast:31 row_mask:0xc bank_mask:0xf
	v_readlane_b32 s98, v68, 63
	v_readlane_b32 s52, v142, 63
	v_readlane_b32 s99, v69, 63
	v_readlane_b32 s53, v143, 63
	s_nop 0
	v_pk_add_f32 v[66:67], s[98:99], v[68:69] neg_lo:[0,1] neg_hi:[0,1]
	v_pk_add_f32 v[140:141], s[52:53], v[142:143] neg_lo:[0,1] neg_hi:[0,1]
	v_mul_f32_e64 v64, s98, v228
	v_mul_f32_e64 v138, s52, v228
	v_mul_f32_e64 v65, s99, v228
	v_mul_f32_e64 v139, s53, v228
	v_pk_mul_f32 v[66:67], v[66:67], v[228:229]
	v_pk_mul_f32 v[140:141], v[140:141], v[228:229]
	v_exp_f32_e32 v64, v64
	v_exp_f32_e32 v138, v138
	v_exp_f32_e32 v65, v65
	v_exp_f32_e32 v139, v139
	v_exp_f32_e32 v66, v66
	v_exp_f32_e32 v140, v140
	v_exp_f32_e32 v67, v67
	v_exp_f32_e32 v141, v141
	v_lshlrev_b32_e32 v70, 16, v24
	v_lshlrev_b32_e32 v144, 16, v25
	v_and_b32_e32 v71, 0xffff0000, v24
	v_and_b32_e32 v145, 0xffff0000, v25
	v_pk_mul_f32 v[66:67], v[66:67], v[70:71]
	v_pk_mul_f32 v[140:141], v[140:141], v[144:145]
	v_cvt_pk_bf16_f32 v70, v66, v67
	v_cvt_pk_bf16_f32 v144, v140, v141
	v_cvt_pk_bf16_f32 v244, v0, v1
	v_cvt_pk_bf16_f32 v245, v2, v3
	v_cvt_pk_bf16_f32 v246, v4, v5
	v_cvt_pk_bf16_f32 v247, v6, v7
	global_store_dwordx2 v234, v[244:245], s[100:101]
	global_store_dwordx2 v235, v[246:247], s[100:101]
	s_add_u32 s100, s100, 0x40000
	s_addc_u32 s101, s101, 0
	ds_write_b16 v172, v70 offset:0
	ds_write_b16_d16_hi v172, v70 offset:128
	ds_write_b16 v172, v144 offset:2048
	ds_write_b16_d16_hi v172, v144 offset:2176
	s_and_saveexec_b64 s[20:21], vcc
	ds_write_b64 v163, v[64:65] offset:8192
	ds_write_b64 v163, v[138:139] offset:8256
	s_mov_b64 exec, s[20:21]
	s_waitcnt vmcnt(28)
	ds_write_b64 v28, v[152:153] offset:10240
	ds_write_b32 v30, v158 offset:4160
	ds_write_b64 v28, v[166:167] offset:15360
	ds_write_b32 v30, v159 offset:6240
	s_waitcnt lgkmcnt(0)
	s_barrier
	ds_read_b128 v[8:11], v29 offset:10240
	ds_read_b128 v[12:15], v29 offset:10256
	ds_read_b128 v[16:19], v29 offset:10272
	ds_read_b128 v[20:23], v29 offset:10288
	ds_read_b32 v24, v31 offset:4160
	ds_read_b128 v[32:35], v29 offset:15360
	ds_read_b128 v[36:39], v29 offset:15376
	ds_read_b128 v[40:43], v29 offset:15392
	ds_read_b128 v[44:47], v29 offset:15408
	ds_read_b32 v25, v31 offset:6240
	global_load_dwordx2 v[152:153], v230, s[26:27]
	global_load_dword v158, v231, s[58:59]
	s_add_u32 s26, s26, 0x1000
	s_addc_u32 s27, s27, 0
	s_add_u32 s58, s58, 0x10000
	s_addc_u32 s59, s59, 0
	global_load_dwordx2 v[166:167], v230, s[26:27]
	global_load_dword v159, v231, s[58:59]
	s_add_u32 s26, s26, 0x1000
	s_addc_u32 s27, s27, 0
	s_add_u32 s58, s58, 0x10000
	s_addc_u32 s59, s59, 0
	global_load_dwordx4 v[48:51], v232, s[34:35]
	global_load_dwordx4 v[52:55], v233, s[34:35]
	global_load_dwordx4 v[56:59], v232, s[34:35] offset:1024
	global_load_dwordx4 v[60:63], v233, s[34:35] offset:1024
	s_add_u32 s34, s34, 0x8000
	s_addc_u32 s35, s35, 0
	global_load_dwordx4 v[122:125], v232, s[34:35]
	global_load_dwordx4 v[126:129], v233, s[34:35]
	global_load_dwordx4 v[130:133], v232, s[34:35] offset:1024
	global_load_dwordx4 v[134:137], v233, s[34:35] offset:1024
	s_add_u32 s34, s34, 0x8000
	s_addc_u32 s35, s35, 0
	ds_read_b128 v[154:157], v75 offset:0
	ds_read_b128 v[240:243], v164 offset:8192
	ds_read_b128 v[236:239], v75 offset:64
	s_waitcnt lgkmcnt(3)
; #define MFMA16(a, b, c) __builtin_amdgcn_mfma_f32_16x16x32_bf16((a), (b), (c), 0, 0, 0)
; DI bf16_t f2bf(float x) { return (bf16_t)(pk2(x, 0.f) & 0xffffu); }
; DI float bf2f(unsigned x) { return __uint_as_float(x << 16); }
;     ...
; #pragma unroll
;             for (int e = 0; e < 2; ++e) {
;                 float z = bb[e];
; #pragma unroll
;                 for (int q = 0; q < 4; ++q) { z += a4[q].x * wa[e][4 * q] + a4[q].y * wa[e][4 * q + 1] + a4[q].z * wa[e][4 * q + 2] + a4[q].w * wa[e][4 * q + 3]; }
;                 cum[e] = (fminf(z, 0.f) - __logf(1.f + __expf(-fabsf(z)))) * (1.f / 16.f);
;             }
; #pragma unroll
;             for (int o = 1; o < 64; o <<= 1) {
;                 const float t0 = __shfl_up(cum[0], o), t1 = __shfl_up(cum[1], o);
;                 if (l >= o) { cum[0] += t0; cum[1] += t1; }
;             }
;             const float tot0 = __shfl(cum[0], 63), tot1 = __shfl(cum[1], 63);
;             kdl[(buf * 16 + 2 * w) * 64 + l] = f2bf(bf2f(kraw & 0xffffu) * __expf(tot0 - cum[0]));
;             kdl[(buf * 16 + 2 * w + 1) * 64 + l] = f2bf(bf2f(kraw >> 16) * __expf(tot1 - cum[1]));
;             if (l == 0) { decl[buf * 16 + 2 * w] = __expf(tot0); decl[buf * 16 + 2 * w + 1] = __expf(tot1); }
;             __syncthreads();
;             const f32x4 d4 = *(const f32x4*)(decl + buf * 16 + (l >> 4) * 4);
; #pragma unroll
;             for (int e = 0; e < 2; ++e) acc[e] = acc[e] * d4;
; #pragma unroll
;             for (int ks = 0; ks < 2; ++ks) {
;                 const bf16x8 af = *(const bf16x8*)(kdl + (buf * 16 + (l & 15)) * 64 + ks * 32 + (l >> 4) * 8);
; #pragma unroll
;                 for (int e = 0; e < 2; ++e) acc[e] = MFMA16(af, vfr[e][ks], acc[e]);
	v_pk_fma_f32 v[64:65], v[8:9], v[86:87], v[118:119] op_sel:[0,0,0] op_sel_hi:[0,1,1]
	v_pk_fma_f32 v[138:139], v[32:33], v[86:87], v[118:119] op_sel:[0,0,0] op_sel_hi:[0,1,1]
	v_pk_mul_f32 v[66:67], v[16:17], v[102:103] op_sel:[0,0] op_sel_hi:[0,1]
	v_pk_mul_f32 v[140:141], v[40:41], v[102:103] op_sel:[0,0] op_sel_hi:[0,1]
	v_pk_fma_f32 v[64:65], v[8:9], v[88:89], v[64:65] op_sel:[1,0,0] op_sel_hi:[1,1,1]
	v_pk_fma_f32 v[138:139], v[32:33], v[88:89], v[138:139] op_sel:[1,0,0] op_sel_hi:[1,1,1]
	v_pk_fma_f32 v[66:67], v[16:17], v[104:105], v[66:67] op_sel:[1,0,0] op_sel_hi:[1,1,1]
	v_pk_fma_f32 v[140:141], v[40:41], v[104:105], v[140:141] op_sel:[1,0,0] op_sel_hi:[1,1,1]
	v_pk_fma_f32 v[64:65], v[10:11], v[90:91], v[64:65] op_sel:[0,0,0] op_sel_hi:[0,1,1]
	v_pk_fma_f32 v[138:139], v[34:35], v[90:91], v[138:139] op_sel:[0,0,0] op_sel_hi:[0,1,1]
	v_pk_fma_f32 v[66:67], v[18:19], v[106:107], v[66:67] op_sel:[0,0,0] op_sel_hi:[0,1,1]
	v_pk_fma_f32 v[140:141], v[42:43], v[106:107], v[140:141] op_sel:[0,0,0] op_sel_hi:[0,1,1]
	v_pk_fma_f32 v[64:65], v[10:11], v[92:93], v[64:65] op_sel:[1,0,0] op_sel_hi:[1,1,1]
	v_pk_fma_f32 v[138:139], v[34:35], v[92:93], v[138:139] op_sel:[1,0,0] op_sel_hi:[1,1,1]
	v_pk_fma_f32 v[66:67], v[18:19], v[108:109], v[66:67] op_sel:[1,0,0] op_sel_hi:[1,1,1]
	v_pk_fma_f32 v[140:141], v[42:43], v[108:109], v[140:141] op_sel:[1,0,0] op_sel_hi:[1,1,1]
	v_pk_fma_f32 v[64:65], v[12:13], v[94:95], v[64:65] op_sel:[0,0,0] op_sel_hi:[0,1,1]
	v_pk_fma_f32 v[138:139], v[36:37], v[94:95], v[138:139] op_sel:[0,0,0] op_sel_hi:[0,1,1]
	v_pk_fma_f32 v[66:67], v[20:21], v[110:111], v[66:67] op_sel:[0,0,0] op_sel_hi:[0,1,1]
	v_pk_fma_f32 v[140:141], v[44:45], v[110:111], v[140:141] op_sel:[0,0,0] op_sel_hi:[0,1,1]
	v_pk_fma_f32 v[64:65], v[12:13], v[96:97], v[64:65] op_sel:[1,0,0] op_sel_hi:[1,1,1]
	v_pk_fma_f32 v[138:139], v[36:37], v[96:97], v[138:139] op_sel:[1,0,0] op_sel_hi:[1,1,1]
	v_pk_fma_f32 v[66:67], v[20:21], v[112:113], v[66:67] op_sel:[1,0,0] op_sel_hi:[1,1,1]
	v_pk_fma_f32 v[140:141], v[44:45], v[112:113], v[140:141] op_sel:[1,0,0] op_sel_hi:[1,1,1]
	v_pk_fma_f32 v[64:65], v[14:15], v[98:99], v[64:65] op_sel:[0,0,0] op_sel_hi:[0,1,1]
	v_pk_fma_f32 v[138:139], v[38:39], v[98:99], v[138:139] op_sel:[0,0,0] op_sel_hi:[0,1,1]
	v_pk_fma_f32 v[66:67], v[22:23], v[114:115], v[66:67] op_sel:[0,0,0] op_sel_hi:[0,1,1]
	v_pk_fma_f32 v[140:141], v[46:47], v[114:115], v[140:141] op_sel:[0,0,0] op_sel_hi:[0,1,1]
	v_pk_fma_f32 v[64:65], v[14:15], v[100:101], v[64:65] op_sel:[1,0,0] op_sel_hi:[1,1,1]
	v_pk_fma_f32 v[138:139], v[38:39], v[100:101], v[138:139] op_sel:[1,0,0] op_sel_hi:[1,1,1]
	v_pk_fma_f32 v[66:67], v[22:23], v[116:117], v[66:67] op_sel:[1,0,0] op_sel_hi:[1,1,1]
	v_pk_fma_f32 v[140:141], v[46:47], v[116:117], v[140:141] op_sel:[1,0,0] op_sel_hi:[1,1,1]
	v_pk_add_f32 v[64:65], v[64:65], v[66:67]
	v_pk_add_f32 v[138:139], v[138:139], v[140:141]
	s_waitcnt lgkmcnt(0)
	v_pk_mul_f32 v[0:1], v[0:1], v[240:241]
	v_pk_mul_f32 v[2:3], v[2:3], v[242:243]
	v_pk_mul_f32 v[4:5], v[4:5], v[240:241]
	v_pk_mul_f32 v[6:7], v[6:7], v[242:243]
	s_waitcnt vmcnt(16)
	s_nop 0
	v_mfma_f32_16x16x32_bf16 v[0:3], v[154:157], v[178:181], v[0:3]
	v_mfma_f32_16x16x32_bf16 v[4:7], v[154:157], v[186:189], v[4:7]
	v_mfma_f32_16x16x32_bf16 v[0:3], v[236:239], v[182:185], v[0:3]
	v_mfma_f32_16x16x32_bf16 v[4:7], v[236:239], v[190:193], v[4:7]
	ds_read_b128 v[154:157], v75 offset:2048
	ds_read_b128 v[240:243], v164 offset:8256
	ds_read_b128 v[236:239], v75 offset:2112
	v_mul_f32_e64 v66, |v64|, v220
	v_mul_f32_e64 v140, |v138|, v220
	v_mul_f32_e64 v67, |v65|, v220
	v_mul_f32_e64 v141, |v139|, v220
	v_exp_f32_e32 v66, v66
	v_exp_f32_e32 v140, v140
	v_exp_f32_e32 v67, v67
	v_exp_f32_e32 v141, v141
	v_min_f32_e32 v68, 0, v64
	v_min_f32_e32 v142, 0, v138
	v_min_f32_e32 v69, 0, v65
	v_min_f32_e32 v143, 0, v139
	v_pk_add_f32 v[66:67], v[66:67], v[222:223]
	v_pk_add_f32 v[140:141], v[140:141], v[222:223]
	v_log_f32_e32 v64, v66
	v_log_f32_e32 v138, v140
	v_log_f32_e32 v65, v67
	v_log_f32_e32 v139, v141
	v_pk_mul_f32 v[66:67], v[64:65], v[224:225]
	v_pk_mul_f32 v[140:141], v[138:139], v[224:225]
	v_pk_fma_f32 v[70:71], v[64:65], v[224:225], v[66:67] neg_lo:[0,0,1] neg_hi:[0,0,1]
	v_pk_fma_f32 v[144:145], v[138:139], v[224:225], v[140:141] neg_lo:[0,0,1] neg_hi:[0,0,1]
	v_pk_fma_f32 v[70:71], v[64:65], v[226:227], v[70:71]
	v_pk_fma_f32 v[144:145], v[138:139], v[226:227], v[144:145]
	v_pk_fma_f32 v[70:71], v[64:65], v[224:225], v[70:71]
	v_pk_fma_f32 v[144:145], v[138:139], v[224:225], v[144:145]
	v_pk_add_f32 v[68:69], v[68:69], v[70:71] neg_lo:[0,1] neg_hi:[0,1]
	v_pk_add_f32 v[142:143], v[142:143], v[144:145] neg_lo:[0,1] neg_hi:[0,1]
	v_pk_mul_f32 v[68:69], v[68:69], v[214:215]
	v_pk_mul_f32 v[142:143], v[142:143], v[214:215]
	v_cvt_pk_bf16_f32 v244, v0, v1
	v_cvt_pk_bf16_f32 v245, v2, v3
	v_cvt_pk_bf16_f32 v246, v4, v5
	v_cvt_pk_bf16_f32 v247, v6, v7
	global_store_dwordx2 v234, v[244:245], s[100:101]
	global_store_dwordx2 v235, v[246:247], s[100:101]
	s_add_u32 s100, s100, 0x40000
	s_addc_u32 s101, s101, 0
	s_waitcnt lgkmcnt(0)
	v_pk_mul_f32 v[0:1], v[0:1], v[240:241]
	v_pk_mul_f32 v[2:3], v[2:3], v[242:243]
	v_pk_mul_f32 v[4:5], v[4:5], v[240:241]
	v_pk_mul_f32 v[6:7], v[6:7], v[242:243]
	s_waitcnt vmcnt(18)
; DI float bf2f(unsigned x) { return __uint_as_float(x << 16); }
;     ...
;         auto ldchunk = [&](int n) {
;             const int tok = b * 4096 + n * 64 + l;
; #pragma unroll
;             for (int q = 0; q < 4; ++q) a4n[q] = *(const f32x4*)(GA + (size_t)tok * 16 + 4 * q);
;             krawn = *(const unsigned*)(GK + (size_t)tok * 512 + kc0);
; #pragma unroll
;             for (int e = 0; e < 2; ++e)
; #pragma unroll
;                 for (int ks = 0; ks < 2; ++ks)
;                     vfrn[e][ks] = *(const bf16x8*)(GVT + ((size_t)(b * 1024 + hh * 256 + (2 * w + e) * 16 + (l & 15))) * 4096 + n * 64 + ks * 32 + (l >> 4) * 8);
;         };
;         ldchunk(0);
;         for (int n = 0; n < 64; ++n) {
;             const int buf = n & 1;
;             f32x4 a4[4]; bf16x8 vfr[2][2];
; #pragma unroll
;             for (int q = 0; q < 4; ++q) a4[q] = a4n[q];
;             const unsigned kraw = krawn;
; #pragma unroll
;             for (int e = 0; e < 2; ++e)
; #pragma unroll
;                 for (int ks = 0; ks < 2; ++ks) vfr[e][ks] = vfrn[e][ks];
;             if (n + 1 < 64) ldchunk(n + 1);
;             float cum[2];
; #pragma unroll
;             for (int e = 0; e < 2; ++e) {
;                 float z = bb[e];
; #pragma unroll
;                 for (int q = 0; q < 4; ++q) { z += a4[q].x * wa[e][4 * q] + a4[q].y * wa[e][4 * q + 1] + a4[q].z * wa[e][4 * q + 2] + a4[q].w * wa[e][4 * q + 3]; }
;                 cum[e] = (fminf(z, 0.f) - __logf(1.f + __expf(-fabsf(z)))) * (1.f / 16.f);
;             }
; #pragma unroll
;             for (int o = 1; o < 64; o <<= 1) {
;                 const float t0 = __shfl_up(cum[0], o), t1 = __shfl_up(cum[1], o);
;                 if (l >= o) { cum[0] += t0; cum[1] += t1; }
;             }
;             const float tot0 = __shfl(cum[0], 63), tot1 = __shfl(cum[1], 63);
;             kdl[(buf * 16 + 2 * w) * 64 + l] = f2bf(bf2f(kraw & 0xffffu) * __expf(tot0 - cum[0]));
;             kdl[(buf * 16 + 2 * w + 1) * 64 + l] = f2bf(bf2f(kraw >> 16) * __expf(tot1 - cum[1]));
;             if (l == 0) { decl[buf * 16 + 2 * w] = __expf(tot0); decl[buf * 16 + 2 * w + 1] = __expf(tot1); }
;             __syncthreads();
;             const f32x4 d4 = *(const f32x4*)(decl + buf * 16 + (l >> 4) * 4);
; #pragma unroll
;             for (int e = 0; e < 2; ++e) acc[e] = acc[e] * d4;
; #pragma unroll
;             for (int ks = 0; ks < 2; ++ks) {
	s_nop 0
	v_mfma_f32_16x16x32_bf16 v[0:3], v[154:157], v[194:197], v[0:3]
	v_mfma_f32_16x16x32_bf16 v[4:7], v[154:157], v[202:205], v[4:7]
	v_mfma_f32_16x16x32_bf16 v[0:3], v[236:239], v[198:201], v[0:3]
	v_mfma_f32_16x16x32_bf16 v[4:7], v[236:239], v[206:209], v[4:7]
	v_add_f32_dpp v68, v68, v68 row_shr:1 row_mask:0xf bank_mask:0xf
	v_add_f32_dpp v142, v142, v142 row_shr:1 row_mask:0xf bank_mask:0xf
	v_add_f32_dpp v69, v69, v69 row_shr:1 row_mask:0xf bank_mask:0xf
	v_add_f32_dpp v143, v143, v143 row_shr:1 row_mask:0xf bank_mask:0xf
	v_add_f32_dpp v68, v68, v68 row_shr:2 row_mask:0xf bank_mask:0xf
	v_add_f32_dpp v142, v142, v142 row_shr:2 row_mask:0xf bank_mask:0xf
	v_add_f32_dpp v69, v69, v69 row_shr:2 row_mask:0xf bank_mask:0xf
	v_add_f32_dpp v143, v143, v143 row_shr:2 row_mask:0xf bank_mask:0xf
	v_add_f32_dpp v68, v68, v68 row_shr:4 row_mask:0xf bank_mask:0xf
	v_add_f32_dpp v142, v142, v142 row_shr:4 row_mask:0xf bank_mask:0xf
	v_add_f32_dpp v69, v69, v69 row_shr:4 row_mask:0xf bank_mask:0xf
	v_add_f32_dpp v143, v143, v143 row_shr:4 row_mask:0xf bank_mask:0xf
	v_add_f32_dpp v68, v68, v68 row_shr:8 row_mask:0xf bank_mask:0xf
	v_add_f32_dpp v142, v142, v142 row_shr:8 row_mask:0xf bank_mask:0xf
	v_add_f32_dpp v69, v69, v69 row_shr:8 row_mask:0xf bank_mask:0xf
	v_add_f32_dpp v143, v143, v143 row_shr:8 row_mask:0xf bank_mask:0xf
	v_add_f32_dpp v68, v68, v68 row_bcast:15 row_mask:0xa bank_mask:0xf
	v_add_f32_dpp v142, v142, v142 row_bcast:15 row_mask:0xa bank_mask:0xf
	v_add_f32_dpp v69, v69, v69 row_bcast:15 row_mask:0xa bank_mask:0xf
	v_add_f32_dpp v143, v143, v143 row_bcast:15 row_mask:0xa bank_mask:0xf
	v_add_f32_dpp v68, v68, v68 row_bcast:31 row_mask:0xc bank_mask:0xf
	v_add_f32_dpp v142, v142, v142 row_bcast:31 row_mask:0xc bank_mask:0xf
	v_add_f32_dpp v69, v69, v69 row_bcast:31 row_mask:0xc bank_mask:0xf
	v_add_f32_dpp v143, v143, v143 row_bcast:31 row_mask:0xc bank_mask:0xf
	v_readlane_b32 s98, v68, 63
	v_readlane_b32 s52, v142, 63
	v_readlane_b32 s99, v69, 63
	v_readlane_b32 s53, v143, 63
	s_nop 0
	v_pk_add_f32 v[66:67], s[98:99], v[68:69] neg_lo:[0,1] neg_hi:[0,1]
	v_pk_add_f32 v[140:141], s[52:53], v[142:143] neg_lo:[0,1] neg_hi:[0,1]
	v_mul_f32_e64 v64, s98, v228
	v_mul_f32_e64 v138, s52, v228
	v_mul_f32_e64 v65, s99, v228
	v_mul_f32_e64 v139, s53, v228
	v_pk_mul_f32 v[66:67], v[66:67], v[228:229]
	v_pk_mul_f32 v[140:141], v[140:141], v[228:229]
	v_exp_f32_e32 v64, v64
	v_exp_f32_e32 v138, v138
	v_exp_f32_e32 v65, v65
	v_exp_f32_e32 v139, v139
	v_exp_f32_e32 v66, v66
	v_exp_f32_e32 v140, v140
	v_exp_f32_e32 v67, v67
	v_exp_f32_e32 v141, v141
	v_lshlrev_b32_e32 v70, 16, v24
	v_lshlrev_b32_e32 v144, 16, v25
	v_and_b32_e32 v71, 0xffff0000, v24
	v_and_b32_e32 v145, 0xffff0000, v25
	v_pk_mul_f32 v[66:67], v[66:67], v[70:71]
	v_pk_mul_f32 v[140:141], v[140:141], v[144:145]
	v_cvt_pk_bf16_f32 v70, v66, v67
	v_cvt_pk_bf16_f32 v144, v140, v141
	v_cvt_pk_bf16_f32 v244, v0, v1
	v_cvt_pk_bf16_f32 v245, v2, v3
	v_cvt_pk_bf16_f32 v246, v4, v5
	v_cvt_pk_bf16_f32 v247, v6, v7
	global_store_dwordx2 v234, v[244:245], s[100:101]
	global_store_dwordx2 v235, v[246:247], s[100:101]
	s_add_u32 s100, s100, 0x40000
	s_addc_u32 s101, s101, 0
	ds_write_b16 v172, v70 offset:4096
	ds_write_b16_d16_hi v172, v70 offset:4224
	ds_write_b16 v172, v144 offset:6144
	ds_write_b16_d16_hi v172, v144 offset:6272
	s_and_saveexec_b64 s[20:21], vcc
	ds_write_b64 v163, v[64:65] offset:8320
	ds_write_b64 v163, v[138:139] offset:8384
	s_mov_b64 exec, s[20:21]
	s_waitcnt vmcnt(28)
	ds_write_b64 v28, v[146:147] offset:0
	ds_write_b32 v30, v150 offset:0
	ds_write_b64 v28, v[148:149] offset:5120
	ds_write_b32 v30, v151 offset:2080
	s_waitcnt lgkmcnt(0)
	s_barrier
	ds_read_b128 v[8:11], v29 offset:0
	ds_read_b128 v[12:15], v29 offset:16
	ds_read_b128 v[16:19], v29 offset:32
	ds_read_b128 v[20:23], v29 offset:48
	ds_read_b32 v24, v31 offset:0
	ds_read_b128 v[32:35], v29 offset:5120
	ds_read_b128 v[36:39], v29 offset:5136
	ds_read_b128 v[40:43], v29 offset:5152
	ds_read_b128 v[44:47], v29 offset:5168
	ds_read_b32 v25, v31 offset:2080
	s_mov_b32 s28, 13
.Lgscan_loop:
	global_load_dwordx2 v[146:147], v230, s[26:27]
	global_load_dword v150, v231, s[58:59]
	s_add_u32 s26, s26, 0x1000
	s_addc_u32 s27, s27, 0
	s_add_u32 s58, s58, 0x10000
	s_addc_u32 s59, s59, 0
	global_load_dwordx2 v[148:149], v230, s[26:27]
	global_load_dword v151, v231, s[58:59]
	s_add_u32 s26, s26, 0x1000
	s_addc_u32 s27, s27, 0
	s_add_u32 s58, s58, 0x10000
	s_addc_u32 s59, s59, 0
	global_load_dwordx4 v[178:181], v232, s[34:35]
	global_load_dwordx4 v[182:185], v233, s[34:35]
	global_load_dwordx4 v[186:189], v232, s[34:35] offset:1024
	global_load_dwordx4 v[190:193], v233, s[34:35] offset:1024
	s_add_u32 s34, s34, 0x8000
	s_addc_u32 s35, s35, 0
	global_load_dwordx4 v[194:197], v232, s[34:35]
	global_load_dwordx4 v[198:201], v233, s[34:35]
	global_load_dwordx4 v[202:205], v232, s[34:35] offset:1024
	global_load_dwordx4 v[206:209], v233, s[34:35] offset:1024
	s_add_u32 s34, s34, 0x8000
	s_addc_u32 s35, s35, 0
	ds_read_b128 v[154:157], v75 offset:4096
	ds_read_b128 v[240:243], v164 offset:8320
	ds_read_b128 v[236:239], v75 offset:4160
	s_waitcnt lgkmcnt(3)
; #define MFMA16(a, b, c) __builtin_amdgcn_mfma_f32_16x16x32_bf16((a), (b), (c), 0, 0, 0)
; DI bf16_t f2bf(float x) { return (bf16_t)(pk2(x, 0.f) & 0xffffu); }
; DI float bf2f(unsigned x) { return __uint_as_float(x << 16); }
;     ...
; #pragma unroll
;             for (int e = 0; e < 2; ++e) {
;                 float z = bb[e];
; #pragma unroll
;                 for (int q = 0; q < 4; ++q) { z += a4[q].x * wa[e][4 * q] + a4[q].y * wa[e][4 * q + 1] + a4[q].z * wa[e][4 * q + 2] + a4[q].w * wa[e][4 * q + 3]; }
;                 cum[e] = (fminf(z, 0.f) - __logf(1.f + __expf(-fabsf(z)))) * (1.f / 16.f);
;             }
; #pragma unroll
;             for (int o = 1; o < 64; o <<= 1) {
;                 const float t0 = __shfl_up(cum[0], o), t1 = __shfl_up(cum[1], o);
;                 if (l >= o) { cum[0] += t0; cum[1] += t1; }
;             }
;             const float tot0 = __shfl(cum[0], 63), tot1 = __shfl(cum[1], 63);
;             kdl[(buf * 16 + 2 * w) * 64 + l] = f2bf(bf2f(kraw & 0xffffu) * __expf(tot0 - cum[0]));
;             kdl[(buf * 16 + 2 * w + 1) * 64 + l] = f2bf(bf2f(kraw >> 16) * __expf(tot1 - cum[1]));
;             if (l == 0) { decl[buf * 16 + 2 * w] = __expf(tot0); decl[buf * 16 + 2 * w + 1] = __expf(tot1); }
;             __syncthreads();
;             const f32x4 d4 = *(const f32x4*)(decl + buf * 16 + (l >> 4) * 4);
; #pragma unroll
;             for (int e = 0; e < 2; ++e) acc[e] = acc[e] * d4;
; #pragma unroll
;             for (int ks = 0; ks < 2; ++ks) {
;                 const bf16x8 af = *(const bf16x8*)(kdl + (buf * 16 + (l & 15)) * 64 + ks * 32 + (l >> 4) * 8);
; #pragma unroll
;                 for (int e = 0; e < 2; ++e) acc[e] = MFMA16(af, vfr[e][ks], acc[e]);
	v_pk_fma_f32 v[64:65], v[8:9], v[86:87], v[118:119] op_sel:[0,0,0] op_sel_hi:[0,1,1]
	v_pk_fma_f32 v[138:139], v[32:33], v[86:87], v[118:119] op_sel:[0,0,0] op_sel_hi:[0,1,1]
	v_pk_mul_f32 v[66:67], v[16:17], v[102:103] op_sel:[0,0] op_sel_hi:[0,1]
	v_pk_mul_f32 v[140:141], v[40:41], v[102:103] op_sel:[0,0] op_sel_hi:[0,1]
	v_pk_fma_f32 v[64:65], v[8:9], v[88:89], v[64:65] op_sel:[1,0,0] op_sel_hi:[1,1,1]
	v_pk_fma_f32 v[138:139], v[32:33], v[88:89], v[138:139] op_sel:[1,0,0] op_sel_hi:[1,1,1]
	v_pk_fma_f32 v[66:67], v[16:17], v[104:105], v[66:67] op_sel:[1,0,0] op_sel_hi:[1,1,1]
	v_pk_fma_f32 v[140:141], v[40:41], v[104:105], v[140:141] op_sel:[1,0,0] op_sel_hi:[1,1,1]
	v_pk_fma_f32 v[64:65], v[10:11], v[90:91], v[64:65] op_sel:[0,0,0] op_sel_hi:[0,1,1]
	v_pk_fma_f32 v[138:139], v[34:35], v[90:91], v[138:139] op_sel:[0,0,0] op_sel_hi:[0,1,1]
	v_pk_fma_f32 v[66:67], v[18:19], v[106:107], v[66:67] op_sel:[0,0,0] op_sel_hi:[0,1,1]
	v_pk_fma_f32 v[140:141], v[42:43], v[106:107], v[140:141] op_sel:[0,0,0] op_sel_hi:[0,1,1]
	v_pk_fma_f32 v[64:65], v[10:11], v[92:93], v[64:65] op_sel:[1,0,0] op_sel_hi:[1,1,1]
	v_pk_fma_f32 v[138:139], v[34:35], v[92:93], v[138:139] op_sel:[1,0,0] op_sel_hi:[1,1,1]
	v_pk_fma_f32 v[66:67], v[18:19], v[108:109], v[66:67] op_sel:[1,0,0] op_sel_hi:[1,1,1]
	v_pk_fma_f32 v[140:141], v[42:43], v[108:109], v[140:141] op_sel:[1,0,0] op_sel_hi:[1,1,1]
	v_pk_fma_f32 v[64:65], v[12:13], v[94:95], v[64:65] op_sel:[0,0,0] op_sel_hi:[0,1,1]
	v_pk_fma_f32 v[138:139], v[36:37], v[94:95], v[138:139] op_sel:[0,0,0] op_sel_hi:[0,1,1]
	v_pk_fma_f32 v[66:67], v[20:21], v[110:111], v[66:67] op_sel:[0,0,0] op_sel_hi:[0,1,1]
	v_pk_fma_f32 v[140:141], v[44:45], v[110:111], v[140:141] op_sel:[0,0,0] op_sel_hi:[0,1,1]
	v_pk_fma_f32 v[64:65], v[12:13], v[96:97], v[64:65] op_sel:[1,0,0] op_sel_hi:[1,1,1]
	v_pk_fma_f32 v[138:139], v[36:37], v[96:97], v[138:139] op_sel:[1,0,0] op_sel_hi:[1,1,1]
	v_pk_fma_f32 v[66:67], v[20:21], v[112:113], v[66:67] op_sel:[1,0,0] op_sel_hi:[1,1,1]
	v_pk_fma_f32 v[140:141], v[44:45], v[112:113], v[140:141] op_sel:[1,0,0] op_sel_hi:[1,1,1]
	v_pk_fma_f32 v[64:65], v[14:15], v[98:99], v[64:65] op_sel:[0,0,0] op_sel_hi:[0,1,1]
	v_pk_fma_f32 v[138:139], v[38:39], v[98:99], v[138:139] op_sel:[0,0,0] op_sel_hi:[0,1,1]
	v_pk_fma_f32 v[66:67], v[22:23], v[114:115], v[66:67] op_sel:[0,0,0] op_sel_hi:[0,1,1]
	v_pk_fma_f32 v[140:141], v[46:47], v[114:115], v[140:141] op_sel:[0,0,0] op_sel_hi:[0,1,1]
	v_pk_fma_f32 v[64:65], v[14:15], v[100:101], v[64:65] op_sel:[1,0,0] op_sel_hi:[1,1,1]
	v_pk_fma_f32 v[138:139], v[38:39], v[100:101], v[138:139] op_sel:[1,0,0] op_sel_hi:[1,1,1]
	v_pk_fma_f32 v[66:67], v[22:23], v[116:117], v[66:67] op_sel:[1,0,0] op_sel_hi:[1,1,1]
	v_pk_fma_f32 v[140:141], v[46:47], v[116:117], v[140:141] op_sel:[1,0,0] op_sel_hi:[1,1,1]
	v_pk_add_f32 v[64:65], v[64:65], v[66:67]
	v_pk_add_f32 v[138:139], v[138:139], v[140:141]
	s_waitcnt lgkmcnt(0)
	v_pk_mul_f32 v[0:1], v[0:1], v[240:241]
	v_pk_mul_f32 v[2:3], v[2:3], v[242:243]
	v_pk_mul_f32 v[4:5], v[4:5], v[240:241]
	v_pk_mul_f32 v[6:7], v[6:7], v[242:243]
	s_waitcnt vmcnt(16)
	s_nop 0
	v_mfma_f32_16x16x32_bf16 v[0:3], v[154:157], v[48:51], v[0:3]
	v_mfma_f32_16x16x32_bf16 v[4:7], v[154:157], v[56:59], v[4:7]
	v_mfma_f32_16x16x32_bf16 v[0:3], v[236:239], v[52:55], v[0:3]
	v_mfma_f32_16x16x32_bf16 v[4:7], v[236:239], v[60:63], v[4:7]
	ds_read_b128 v[154:157], v75 offset:6144
	ds_read_b128 v[240:243], v164 offset:8384
	ds_read_b128 v[236:239], v75 offset:6208
	v_mul_f32_e64 v66, |v64|, v220
	v_mul_f32_e64 v140, |v138|, v220
	v_mul_f32_e64 v67, |v65|, v220
	v_mul_f32_e64 v141, |v139|, v220
	v_exp_f32_e32 v66, v66
	v_exp_f32_e32 v140, v140
	v_exp_f32_e32 v67, v67
	v_exp_f32_e32 v141, v141
	v_min_f32_e32 v68, 0, v64
	v_min_f32_e32 v142, 0, v138
	v_min_f32_e32 v69, 0, v65
	v_min_f32_e32 v143, 0, v139
	v_pk_add_f32 v[66:67], v[66:67], v[222:223]
	v_pk_add_f32 v[140:141], v[140:141], v[222:223]
	v_log_f32_e32 v64, v66
	v_log_f32_e32 v138, v140
	v_log_f32_e32 v65, v67
	v_log_f32_e32 v139, v141
	v_pk_mul_f32 v[66:67], v[64:65], v[224:225]
	v_pk_mul_f32 v[140:141], v[138:139], v[224:225]
	v_pk_fma_f32 v[70:71], v[64:65], v[224:225], v[66:67] neg_lo:[0,0,1] neg_hi:[0,0,1]
	v_pk_fma_f32 v[144:145], v[138:139], v[224:225], v[140:141] neg_lo:[0,0,1] neg_hi:[0,0,1]
	v_pk_fma_f32 v[70:71], v[64:65], v[226:227], v[70:71]
	v_pk_fma_f32 v[144:145], v[138:139], v[226:227], v[144:145]
	v_pk_fma_f32 v[70:71], v[64:65], v[224:225], v[70:71]
	v_pk_fma_f32 v[144:145], v[138:139], v[224:225], v[144:145]
	v_pk_add_f32 v[68:69], v[68:69], v[70:71] neg_lo:[0,1] neg_hi:[0,1]
	v_pk_add_f32 v[142:143], v[142:143], v[144:145] neg_lo:[0,1] neg_hi:[0,1]
	v_pk_mul_f32 v[68:69], v[68:69], v[214:215]
	v_pk_mul_f32 v[142:143], v[142:143], v[214:215]
	v_cvt_pk_bf16_f32 v244, v0, v1
	v_cvt_pk_bf16_f32 v245, v2, v3
	v_cvt_pk_bf16_f32 v246, v4, v5
	v_cvt_pk_bf16_f32 v247, v6, v7
	global_store_dwordx2 v234, v[244:245], s[100:101]
	global_store_dwordx2 v235, v[246:247], s[100:101]
	s_add_u32 s100, s100, 0x40000
	s_addc_u32 s101, s101, 0
	s_waitcnt lgkmcnt(0)
	v_pk_mul_f32 v[0:1], v[0:1], v[240:241]
	v_pk_mul_f32 v[2:3], v[2:3], v[242:243]
	v_pk_mul_f32 v[4:5], v[4:5], v[240:241]
	v_pk_mul_f32 v[6:7], v[6:7], v[242:243]
	s_waitcnt vmcnt(18)
; DI float bf2f(unsigned x) { return __uint_as_float(x << 16); }
;     ...
;         auto ldchunk = [&](int n) {
;             const int tok = b * 4096 + n * 64 + l;
; #pragma unroll
;             for (int q = 0; q < 4; ++q) a4n[q] = *(const f32x4*)(GA + (size_t)tok * 16 + 4 * q);
;             krawn = *(const unsigned*)(GK + (size_t)tok * 512 + kc0);
; #pragma unroll
;             for (int e = 0; e < 2; ++e)
; #pragma unroll
;                 for (int ks = 0; ks < 2; ++ks)
;                     vfrn[e][ks] = *(const bf16x8*)(GVT + ((size_t)(b * 1024 + hh * 256 + (2 * w + e) * 16 + (l & 15))) * 4096 + n * 64 + ks * 32 + (l >> 4) * 8);
;         };
;         ldchunk(0);
;         for (int n = 0; n < 64; ++n) {
;             const int buf = n & 1;
;             f32x4 a4[4]; bf16x8 vfr[2][2];
; #pragma unroll
;             for (int q = 0; q < 4; ++q) a4[q] = a4n[q];
;             const unsigned kraw = krawn;
; #pragma unroll
;             for (int e = 0; e < 2; ++e)
; #pragma unroll
;                 for (int ks = 0; ks < 2; ++ks) vfr[e][ks] = vfrn[e][ks];
;             if (n + 1 < 64) ldchunk(n + 1);
;             float cum[2];
; #pragma unroll
;             for (int e = 0; e < 2; ++e) {
;                 float z = bb[e];
; #pragma unroll
;                 for (int q = 0; q < 4; ++q) { z += a4[q].x * wa[e][4 * q] + a4[q].y * wa[e][4 * q + 1] + a4[q].z * wa[e][4 * q + 2] + a4[q].w * wa[e][4 * q + 3]; }
;                 cum[e] = (fminf(z, 0.f) - __logf(1.f + __expf(-fabsf(z)))) * (1.f / 16.f);
;             }
; #pragma unroll
;             for (int o = 1; o < 64; o <<= 1) {
;                 const float t0 = __shfl_up(cum[0], o), t1 = __shfl_up(cum[1], o);
;                 if (l >= o) { cum[0] += t0; cum[1] += t1; }
;             }
;             const float tot0 = __shfl(cum[0], 63), tot1 = __shfl(cum[1], 63);
;             kdl[(buf * 16 + 2 * w) * 64 + l] = f2bf(bf2f(kraw & 0xffffu) * __expf(tot0 - cum[0]));
;             kdl[(buf * 16 + 2 * w + 1) * 64 + l] = f2bf(bf2f(kraw >> 16) * __expf(tot1 - cum[1]));
;             if (l == 0) { decl[buf * 16 + 2 * w] = __expf(tot0); decl[buf * 16 + 2 * w + 1] = __expf(tot1); }
;             __syncthreads();
;             const f32x4 d4 = *(const f32x4*)(decl + buf * 16 + (l >> 4) * 4);
; #pragma unroll
;             for (int e = 0; e < 2; ++e) acc[e] = acc[e] * d4;
; #pragma unroll
;             for (int ks = 0; ks < 2; ++ks) {
	s_nop 0
	v_mfma_f32_16x16x32_bf16 v[0:3], v[154:157], v[122:125], v[0:3]
	v_mfma_f32_16x16x32_bf16 v[4:7], v[154:157], v[130:133], v[4:7]
	v_mfma_f32_16x16x32_bf16 v[0:3], v[236:239], v[126:129], v[0:3]
	v_mfma_f32_16x16x32_bf16 v[4:7], v[236:239], v[134:137], v[4:7]
	v_add_f32_dpp v68, v68, v68 row_shr:1 row_mask:0xf bank_mask:0xf
	v_add_f32_dpp v142, v142, v142 row_shr:1 row_mask:0xf bank_mask:0xf
	v_add_f32_dpp v69, v69, v69 row_shr:1 row_mask:0xf bank_mask:0xf
	v_add_f32_dpp v143, v143, v143 row_shr:1 row_mask:0xf bank_mask:0xf
	v_add_f32_dpp v68, v68, v68 row_shr:2 row_mask:0xf bank_mask:0xf
	v_add_f32_dpp v142, v142, v142 row_shr:2 row_mask:0xf bank_mask:0xf
	v_add_f32_dpp v69, v69, v69 row_shr:2 row_mask:0xf bank_mask:0xf
	v_add_f32_dpp v143, v143, v143 row_shr:2 row_mask:0xf bank_mask:0xf
	v_add_f32_dpp v68, v68, v68 row_shr:4 row_mask:0xf bank_mask:0xf
	v_add_f32_dpp v142, v142, v142 row_shr:4 row_mask:0xf bank_mask:0xf
	v_add_f32_dpp v69, v69, v69 row_shr:4 row_mask:0xf bank_mask:0xf
	v_add_f32_dpp v143, v143, v143 row_shr:4 row_mask:0xf bank_mask:0xf
	v_add_f32_dpp v68, v68, v68 row_shr:8 row_mask:0xf bank_mask:0xf
	v_add_f32_dpp v142, v142, v142 row_shr:8 row_mask:0xf bank_mask:0xf
	v_add_f32_dpp v69, v69, v69 row_shr:8 row_mask:0xf bank_mask:0xf
	v_add_f32_dpp v143, v143, v143 row_shr:8 row_mask:0xf bank_mask:0xf
	v_add_f32_dpp v68, v68, v68 row_bcast:15 row_mask:0xa bank_mask:0xf
	v_add_f32_dpp v142, v142, v142 row_bcast:15 row_mask:0xa bank_mask:0xf
	v_add_f32_dpp v69, v69, v69 row_bcast:15 row_mask:0xa bank_mask:0xf
	v_add_f32_dpp v143, v143, v143 row_bcast:15 row_mask:0xa bank_mask:0xf
	v_add_f32_dpp v68, v68, v68 row_bcast:31 row_mask:0xc bank_mask:0xf
	v_add_f32_dpp v142, v142, v142 row_bcast:31 row_mask:0xc bank_mask:0xf
	v_add_f32_dpp v69, v69, v69 row_bcast:31 row_mask:0xc bank_mask:0xf
	v_add_f32_dpp v143, v143, v143 row_bcast:31 row_mask:0xc bank_mask:0xf
	v_readlane_b32 s98, v68, 63
	v_readlane_b32 s52, v142, 63
	v_readlane_b32 s99, v69, 63
	v_readlane_b32 s53, v143, 63
	s_nop 0
	v_pk_add_f32 v[66:67], s[98:99], v[68:69] neg_lo:[0,1] neg_hi:[0,1]
	v_pk_add_f32 v[140:141], s[52:53], v[142:143] neg_lo:[0,1] neg_hi:[0,1]
	v_mul_f32_e64 v64, s98, v228
	v_mul_f32_e64 v138, s52, v228
	v_mul_f32_e64 v65, s99, v228
	v_mul_f32_e64 v139, s53, v228
	v_pk_mul_f32 v[66:67], v[66:67], v[228:229]
	v_pk_mul_f32 v[140:141], v[140:141], v[228:229]
	v_exp_f32_e32 v64, v64
	v_exp_f32_e32 v138, v138
	v_exp_f32_e32 v65, v65
	v_exp_f32_e32 v139, v139
	v_exp_f32_e32 v66, v66
	v_exp_f32_e32 v140, v140
	v_exp_f32_e32 v67, v67
	v_exp_f32_e32 v141, v141
	v_lshlrev_b32_e32 v70, 16, v24
	v_lshlrev_b32_e32 v144, 16, v25
	v_and_b32_e32 v71, 0xffff0000, v24
	v_and_b32_e32 v145, 0xffff0000, v25
	v_pk_mul_f32 v[66:67], v[66:67], v[70:71]
	v_pk_mul_f32 v[140:141], v[140:141], v[144:145]
	v_cvt_pk_bf16_f32 v70, v66, v67
	v_cvt_pk_bf16_f32 v144, v140, v141
	v_cvt_pk_bf16_f32 v244, v0, v1
	v_cvt_pk_bf16_f32 v245, v2, v3
	v_cvt_pk_bf16_f32 v246, v4, v5
	v_cvt_pk_bf16_f32 v247, v6, v7
	global_store_dwordx2 v234, v[244:245], s[100:101]
	global_store_dwordx2 v235, v[246:247], s[100:101]
	s_add_u32 s100, s100, 0x40000
	s_addc_u32 s101, s101, 0
	ds_write_b16 v172, v70 offset:0
	ds_write_b16_d16_hi v172, v70 offset:128
	ds_write_b16 v172, v144 offset:2048
	ds_write_b16_d16_hi v172, v144 offset:2176
	s_and_saveexec_b64 s[20:21], vcc
	ds_write_b64 v163, v[64:65] offset:8192
	ds_write_b64 v163, v[138:139] offset:8256
	s_mov_b64 exec, s[20:21]
	s_waitcnt vmcnt(28)
	ds_write_b64 v28, v[152:153] offset:10240
	ds_write_b32 v30, v158 offset:4160
	ds_write_b64 v28, v[166:167] offset:15360
	ds_write_b32 v30, v159 offset:6240
	s_waitcnt lgkmcnt(0)
	s_barrier
	ds_read_b128 v[8:11], v29 offset:10240
	ds_read_b128 v[12:15], v29 offset:10256
	ds_read_b128 v[16:19], v29 offset:10272
	ds_read_b128 v[20:23], v29 offset:10288
	ds_read_b32 v24, v31 offset:4160
	ds_read_b128 v[32:35], v29 offset:15360
	ds_read_b128 v[36:39], v29 offset:15376
	ds_read_b128 v[40:43], v29 offset:15392
	ds_read_b128 v[44:47], v29 offset:15408
	ds_read_b32 v25, v31 offset:6240
	global_load_dwordx2 v[152:153], v230, s[26:27]
	global_load_dword v158, v231, s[58:59]
	s_add_u32 s26, s26, 0x1000
	s_addc_u32 s27, s27, 0
	s_add_u32 s58, s58, 0x10000
	s_addc_u32 s59, s59, 0
	global_load_dwordx2 v[166:167], v230, s[26:27]
	global_load_dword v159, v231, s[58:59]
	s_add_u32 s26, s26, 0x1000
	s_addc_u32 s27, s27, 0
	s_add_u32 s58, s58, 0x10000
	s_addc_u32 s59, s59, 0
	global_load_dwordx4 v[48:51], v232, s[34:35]
	global_load_dwordx4 v[52:55], v233, s[34:35]
	global_load_dwordx4 v[56:59], v232, s[34:35] offset:1024
	global_load_dwordx4 v[60:63], v233, s[34:35] offset:1024
	s_add_u32 s34, s34, 0x8000
	s_addc_u32 s35, s35, 0
	global_load_dwordx4 v[122:125], v232, s[34:35]
	global_load_dwordx4 v[126:129], v233, s[34:35]
	global_load_dwordx4 v[130:133], v232, s[34:35] offset:1024
	global_load_dwordx4 v[134:137], v233, s[34:35] offset:1024
	s_add_u32 s34, s34, 0x8000
	s_addc_u32 s35, s35, 0
	ds_read_b128 v[154:157], v75 offset:0
	ds_read_b128 v[240:243], v164 offset:8192
	ds_read_b128 v[236:239], v75 offset:64
	s_waitcnt lgkmcnt(3)
; #define MFMA16(a, b, c) __builtin_amdgcn_mfma_f32_16x16x32_bf16((a), (b), (c), 0, 0, 0)
; DI bf16_t f2bf(float x) { return (bf16_t)(pk2(x, 0.f) & 0xffffu); }
; DI float bf2f(unsigned x) { return __uint_as_float(x << 16); }
;     ...
; #pragma unroll
;             for (int e = 0; e < 2; ++e) {
;                 float z = bb[e];
; #pragma unroll
;                 for (int q = 0; q < 4; ++q) { z += a4[q].x * wa[e][4 * q] + a4[q].y * wa[e][4 * q + 1] + a4[q].z * wa[e][4 * q + 2] + a4[q].w * wa[e][4 * q + 3]; }
;                 cum[e] = (fminf(z, 0.f) - __logf(1.f + __expf(-fabsf(z)))) * (1.f / 16.f);
;             }
; #pragma unroll
;             for (int o = 1; o < 64; o <<= 1) {
;                 const float t0 = __shfl_up(cum[0], o), t1 = __shfl_up(cum[1], o);
;                 if (l >= o) { cum[0] += t0; cum[1] += t1; }
;             }
;             const float tot0 = __shfl(cum[0], 63), tot1 = __shfl(cum[1], 63);
;             kdl[(buf * 16 + 2 * w) * 64 + l] = f2bf(bf2f(kraw & 0xffffu) * __expf(tot0 - cum[0]));
;             kdl[(buf * 16 + 2 * w + 1) * 64 + l] = f2bf(bf2f(kraw >> 16) * __expf(tot1 - cum[1]));
;             if (l == 0) { decl[buf * 16 + 2 * w] = __expf(tot0); decl[buf * 16 + 2 * w + 1] = __expf(tot1); }
;             __syncthreads();
;             const f32x4 d4 = *(const f32x4*)(decl + buf * 16 + (l >> 4) * 4);
; #pragma unroll
;             for (int e = 0; e < 2; ++e) acc[e] = acc[e] * d4;
; #pragma unroll
;             for (int ks = 0; ks < 2; ++ks) {
;                 const bf16x8 af = *(const bf16x8*)(kdl + (buf * 16 + (l & 15)) * 64 + ks * 32 + (l >> 4) * 8);
; #pragma unroll
;                 for (int e = 0; e < 2; ++e) acc[e] = MFMA16(af, vfr[e][ks], acc[e]);
	v_pk_fma_f32 v[64:65], v[8:9], v[86:87], v[118:119] op_sel:[0,0,0] op_sel_hi:[0,1,1]
	v_pk_fma_f32 v[138:139], v[32:33], v[86:87], v[118:119] op_sel:[0,0,0] op_sel_hi:[0,1,1]
	v_pk_mul_f32 v[66:67], v[16:17], v[102:103] op_sel:[0,0] op_sel_hi:[0,1]
	v_pk_mul_f32 v[140:141], v[40:41], v[102:103] op_sel:[0,0] op_sel_hi:[0,1]
	v_pk_fma_f32 v[64:65], v[8:9], v[88:89], v[64:65] op_sel:[1,0,0] op_sel_hi:[1,1,1]
	v_pk_fma_f32 v[138:139], v[32:33], v[88:89], v[138:139] op_sel:[1,0,0] op_sel_hi:[1,1,1]
	v_pk_fma_f32 v[66:67], v[16:17], v[104:105], v[66:67] op_sel:[1,0,0] op_sel_hi:[1,1,1]
	v_pk_fma_f32 v[140:141], v[40:41], v[104:105], v[140:141] op_sel:[1,0,0] op_sel_hi:[1,1,1]
	v_pk_fma_f32 v[64:65], v[10:11], v[90:91], v[64:65] op_sel:[0,0,0] op_sel_hi:[0,1,1]
	v_pk_fma_f32 v[138:139], v[34:35], v[90:91], v[138:139] op_sel:[0,0,0] op_sel_hi:[0,1,1]
	v_pk_fma_f32 v[66:67], v[18:19], v[106:107], v[66:67] op_sel:[0,0,0] op_sel_hi:[0,1,1]
	v_pk_fma_f32 v[140:141], v[42:43], v[106:107], v[140:141] op_sel:[0,0,0] op_sel_hi:[0,1,1]
	v_pk_fma_f32 v[64:65], v[10:11], v[92:93], v[64:65] op_sel:[1,0,0] op_sel_hi:[1,1,1]
	v_pk_fma_f32 v[138:139], v[34:35], v[92:93], v[138:139] op_sel:[1,0,0] op_sel_hi:[1,1,1]
	v_pk_fma_f32 v[66:67], v[18:19], v[108:109], v[66:67] op_sel:[1,0,0] op_sel_hi:[1,1,1]
	v_pk_fma_f32 v[140:141], v[42:43], v[108:109], v[140:141] op_sel:[1,0,0] op_sel_hi:[1,1,1]
	v_pk_fma_f32 v[64:65], v[12:13], v[94:95], v[64:65] op_sel:[0,0,0] op_sel_hi:[0,1,1]
	v_pk_fma_f32 v[138:139], v[36:37], v[94:95], v[138:139] op_sel:[0,0,0] op_sel_hi:[0,1,1]
	v_pk_fma_f32 v[66:67], v[20:21], v[110:111], v[66:67] op_sel:[0,0,0] op_sel_hi:[0,1,1]
	v_pk_fma_f32 v[140:141], v[44:45], v[110:111], v[140:141] op_sel:[0,0,0] op_sel_hi:[0,1,1]
	v_pk_fma_f32 v[64:65], v[12:13], v[96:97], v[64:65] op_sel:[1,0,0] op_sel_hi:[1,1,1]
	v_pk_fma_f32 v[138:139], v[36:37], v[96:97], v[138:139] op_sel:[1,0,0] op_sel_hi:[1,1,1]
	v_pk_fma_f32 v[66:67], v[20:21], v[112:113], v[66:67] op_sel:[1,0,0] op_sel_hi:[1,1,1]
	v_pk_fma_f32 v[140:141], v[44:45], v[112:113], v[140:141] op_sel:[1,0,0] op_sel_hi:[1,1,1]
	v_pk_fma_f32 v[64:65], v[14:15], v[98:99], v[64:65] op_sel:[0,0,0] op_sel_hi:[0,1,1]
	v_pk_fma_f32 v[138:139], v[38:39], v[98:99], v[138:139] op_sel:[0,0,0] op_sel_hi:[0,1,1]
	v_pk_fma_f32 v[66:67], v[22:23], v[114:115], v[66:67] op_sel:[0,0,0] op_sel_hi:[0,1,1]
	v_pk_fma_f32 v[140:141], v[46:47], v[114:115], v[140:141] op_sel:[0,0,0] op_sel_hi:[0,1,1]
	v_pk_fma_f32 v[64:65], v[14:15], v[100:101], v[64:65] op_sel:[1,0,0] op_sel_hi:[1,1,1]
	v_pk_fma_f32 v[138:139], v[38:39], v[100:101], v[138:139] op_sel:[1,0,0] op_sel_hi:[1,1,1]
	v_pk_fma_f32 v[66:67], v[22:23], v[116:117], v[66:67] op_sel:[1,0,0] op_sel_hi:[1,1,1]
	v_pk_fma_f32 v[140:141], v[46:47], v[116:117], v[140:141] op_sel:[1,0,0] op_sel_hi:[1,1,1]
	v_pk_add_f32 v[64:65], v[64:65], v[66:67]
	v_pk_add_f32 v[138:139], v[138:139], v[140:141]
	s_waitcnt lgkmcnt(0)
	v_pk_mul_f32 v[0:1], v[0:1], v[240:241]
	v_pk_mul_f32 v[2:3], v[2:3], v[242:243]
	v_pk_mul_f32 v[4:5], v[4:5], v[240:241]
	v_pk_mul_f32 v[6:7], v[6:7], v[242:243]
	s_waitcnt vmcnt(16)
	s_nop 0
	v_mfma_f32_16x16x32_bf16 v[0:3], v[154:157], v[178:181], v[0:3]
	v_mfma_f32_16x16x32_bf16 v[4:7], v[154:157], v[186:189], v[4:7]
	v_mfma_f32_16x16x32_bf16 v[0:3], v[236:239], v[182:185], v[0:3]
	v_mfma_f32_16x16x32_bf16 v[4:7], v[236:239], v[190:193], v[4:7]
	ds_read_b128 v[154:157], v75 offset:2048
	ds_read_b128 v[240:243], v164 offset:8256
	ds_read_b128 v[236:239], v75 offset:2112
	v_mul_f32_e64 v66, |v64|, v220
	v_mul_f32_e64 v140, |v138|, v220
	v_mul_f32_e64 v67, |v65|, v220
	v_mul_f32_e64 v141, |v139|, v220
	v_exp_f32_e32 v66, v66
	v_exp_f32_e32 v140, v140
	v_exp_f32_e32 v67, v67
	v_exp_f32_e32 v141, v141
	v_min_f32_e32 v68, 0, v64
	v_min_f32_e32 v142, 0, v138
	v_min_f32_e32 v69, 0, v65
	v_min_f32_e32 v143, 0, v139
	v_pk_add_f32 v[66:67], v[66:67], v[222:223]
	v_pk_add_f32 v[140:141], v[140:141], v[222:223]
	v_log_f32_e32 v64, v66
	v_log_f32_e32 v138, v140
	v_log_f32_e32 v65, v67
	v_log_f32_e32 v139, v141
	v_pk_mul_f32 v[66:67], v[64:65], v[224:225]
	v_pk_mul_f32 v[140:141], v[138:139], v[224:225]
	v_pk_fma_f32 v[70:71], v[64:65], v[224:225], v[66:67] neg_lo:[0,0,1] neg_hi:[0,0,1]
	v_pk_fma_f32 v[144:145], v[138:139], v[224:225], v[140:141] neg_lo:[0,0,1] neg_hi:[0,0,1]
	v_pk_fma_f32 v[70:71], v[64:65], v[226:227], v[70:71]
	v_pk_fma_f32 v[144:145], v[138:139], v[226:227], v[144:145]
	v_pk_fma_f32 v[70:71], v[64:65], v[224:225], v[70:71]
	v_pk_fma_f32 v[144:145], v[138:139], v[224:225], v[144:145]
	v_pk_add_f32 v[68:69], v[68:69], v[70:71] neg_lo:[0,1] neg_hi:[0,1]
	v_pk_add_f32 v[142:143], v[142:143], v[144:145] neg_lo:[0,1] neg_hi:[0,1]
	v_pk_mul_f32 v[68:69], v[68:69], v[214:215]
	v_pk_mul_f32 v[142:143], v[142:143], v[214:215]
	v_cvt_pk_bf16_f32 v244, v0, v1
	v_cvt_pk_bf16_f32 v245, v2, v3
	v_cvt_pk_bf16_f32 v246, v4, v5
	v_cvt_pk_bf16_f32 v247, v6, v7
	global_store_dwordx2 v234, v[244:245], s[100:101]
	global_store_dwordx2 v235, v[246:247], s[100:101]
	s_add_u32 s100, s100, 0x40000
	s_addc_u32 s101, s101, 0
	s_waitcnt lgkmcnt(0)
	v_pk_mul_f32 v[0:1], v[0:1], v[240:241]
	v_pk_mul_f32 v[2:3], v[2:3], v[242:243]
	v_pk_mul_f32 v[4:5], v[4:5], v[240:241]
	v_pk_mul_f32 v[6:7], v[6:7], v[242:243]
	s_waitcnt vmcnt(18)
; DI float bf2f(unsigned x) { return __uint_as_float(x << 16); }
;     ...
;         auto ldchunk = [&](int n) {
;             const int tok = b * 4096 + n * 64 + l;
; #pragma unroll
;             for (int q = 0; q < 4; ++q) a4n[q] = *(const f32x4*)(GA + (size_t)tok * 16 + 4 * q);
;             krawn = *(const unsigned*)(GK + (size_t)tok * 512 + kc0);
; #pragma unroll
;             for (int e = 0; e < 2; ++e)
; #pragma unroll
;                 for (int ks = 0; ks < 2; ++ks)
;                     vfrn[e][ks] = *(const bf16x8*)(GVT + ((size_t)(b * 1024 + hh * 256 + (2 * w + e) * 16 + (l & 15))) * 4096 + n * 64 + ks * 32 + (l >> 4) * 8);
;         };
;         ldchunk(0);
;         for (int n = 0; n < 64; ++n) {
;             const int buf = n & 1;
;             f32x4 a4[4]; bf16x8 vfr[2][2];
; #pragma unroll
;             for (int q = 0; q < 4; ++q) a4[q] = a4n[q];
;             const unsigned kraw = krawn;
; #pragma unroll
;             for (int e = 0; e < 2; ++e)
; #pragma unroll
;                 for (int ks = 0; ks < 2; ++ks) vfr[e][ks] = vfrn[e][ks];
;             if (n + 1 < 64) ldchunk(n + 1);
;             float cum[2];
; #pragma unroll
;             for (int e = 0; e < 2; ++e) {
;                 float z = bb[e];
; #pragma unroll
;                 for (int q = 0; q < 4; ++q) { z += a4[q].x * wa[e][4 * q] + a4[q].y * wa[e][4 * q + 1] + a4[q].z * wa[e][4 * q + 2] + a4[q].w * wa[e][4 * q + 3]; }
;                 cum[e] = (fminf(z, 0.f) - __logf(1.f + __expf(-fabsf(z)))) * (1.f / 16.f);
;             }
; #pragma unroll
;             for (int o = 1; o < 64; o <<= 1) {
;                 const float t0 = __shfl_up(cum[0], o), t1 = __shfl_up(cum[1], o);
;                 if (l >= o) { cum[0] += t0; cum[1] += t1; }
;             }
;             const float tot0 = __shfl(cum[0], 63), tot1 = __shfl(cum[1], 63);
;             kdl[(buf * 16 + 2 * w) * 64 + l] = f2bf(bf2f(kraw & 0xffffu) * __expf(tot0 - cum[0]));
;             kdl[(buf * 16 + 2 * w + 1) * 64 + l] = f2bf(bf2f(kraw >> 16) * __expf(tot1 - cum[1]));
;             if (l == 0) { decl[buf * 16 + 2 * w] = __expf(tot0); decl[buf * 16 + 2 * w + 1] = __expf(tot1); }
;             __syncthreads();
;             const f32x4 d4 = *(const f32x4*)(decl + buf * 16 + (l >> 4) * 4);
; #pragma unroll
;             for (int e = 0; e < 2; ++e) acc[e] = acc[e] * d4;
; #pragma unroll
;             for (int ks = 0; ks < 2; ++ks) {
	s_nop 0
	v_mfma_f32_16x16x32_bf16 v[0:3], v[154:157], v[194:197], v[0:3]
	v_mfma_f32_16x16x32_bf16 v[4:7], v[154:157], v[202:205], v[4:7]
	v_mfma_f32_16x16x32_bf16 v[0:3], v[236:239], v[198:201], v[0:3]
	v_mfma_f32_16x16x32_bf16 v[4:7], v[236:239], v[206:209], v[4:7]
	v_add_f32_dpp v68, v68, v68 row_shr:1 row_mask:0xf bank_mask:0xf
	v_add_f32_dpp v142, v142, v142 row_shr:1 row_mask:0xf bank_mask:0xf
	v_add_f32_dpp v69, v69, v69 row_shr:1 row_mask:0xf bank_mask:0xf
	v_add_f32_dpp v143, v143, v143 row_shr:1 row_mask:0xf bank_mask:0xf
	v_add_f32_dpp v68, v68, v68 row_shr:2 row_mask:0xf bank_mask:0xf
	v_add_f32_dpp v142, v142, v142 row_shr:2 row_mask:0xf bank_mask:0xf
	v_add_f32_dpp v69, v69, v69 row_shr:2 row_mask:0xf bank_mask:0xf
	v_add_f32_dpp v143, v143, v143 row_shr:2 row_mask:0xf bank_mask:0xf
	v_add_f32_dpp v68, v68, v68 row_shr:4 row_mask:0xf bank_mask:0xf
	v_add_f32_dpp v142, v142, v142 row_shr:4 row_mask:0xf bank_mask:0xf
	v_add_f32_dpp v69, v69, v69 row_shr:4 row_mask:0xf bank_mask:0xf
	v_add_f32_dpp v143, v143, v143 row_shr:4 row_mask:0xf bank_mask:0xf
	v_add_f32_dpp v68, v68, v68 row_shr:8 row_mask:0xf bank_mask:0xf
	v_add_f32_dpp v142, v142, v142 row_shr:8 row_mask:0xf bank_mask:0xf
	v_add_f32_dpp v69, v69, v69 row_shr:8 row_mask:0xf bank_mask:0xf
	v_add_f32_dpp v143, v143, v143 row_shr:8 row_mask:0xf bank_mask:0xf
	v_add_f32_dpp v68, v68, v68 row_bcast:15 row_mask:0xa bank_mask:0xf
	v_add_f32_dpp v142, v142, v142 row_bcast:15 row_mask:0xa bank_mask:0xf
	v_add_f32_dpp v69, v69, v69 row_bcast:15 row_mask:0xa bank_mask:0xf
	v_add_f32_dpp v143, v143, v143 row_bcast:15 row_mask:0xa bank_mask:0xf
	v_add_f32_dpp v68, v68, v68 row_bcast:31 row_mask:0xc bank_mask:0xf
	v_add_f32_dpp v142, v142, v142 row_bcast:31 row_mask:0xc bank_mask:0xf
	v_add_f32_dpp v69, v69, v69 row_bcast:31 row_mask:0xc bank_mask:0xf
	v_add_f32_dpp v143, v143, v143 row_bcast:31 row_mask:0xc bank_mask:0xf
	v_readlane_b32 s98, v68, 63
	v_readlane_b32 s52, v142, 63
	v_readlane_b32 s99, v69, 63
	v_readlane_b32 s53, v143, 63
	s_nop 0
	v_pk_add_f32 v[66:67], s[98:99], v[68:69] neg_lo:[0,1] neg_hi:[0,1]
	v_pk_add_f32 v[140:141], s[52:53], v[142:143] neg_lo:[0,1] neg_hi:[0,1]
	v_mul_f32_e64 v64, s98, v228
	v_mul_f32_e64 v138, s52, v228
	v_mul_f32_e64 v65, s99, v228
	v_mul_f32_e64 v139, s53, v228
	v_pk_mul_f32 v[66:67], v[66:67], v[228:229]
	v_pk_mul_f32 v[140:141], v[140:141], v[228:229]
	v_exp_f32_e32 v64, v64
	v_exp_f32_e32 v138, v138
	v_exp_f32_e32 v65, v65
	v_exp_f32_e32 v139, v139
	v_exp_f32_e32 v66, v66
	v_exp_f32_e32 v140, v140
	v_exp_f32_e32 v67, v67
	v_exp_f32_e32 v141, v141
	v_lshlrev_b32_e32 v70, 16, v24
	v_lshlrev_b32_e32 v144, 16, v25
	v_and_b32_e32 v71, 0xffff0000, v24
	v_and_b32_e32 v145, 0xffff0000, v25
	v_pk_mul_f32 v[66:67], v[66:67], v[70:71]
	v_pk_mul_f32 v[140:141], v[140:141], v[144:145]
	v_cvt_pk_bf16_f32 v70, v66, v67
	v_cvt_pk_bf16_f32 v144, v140, v141
	v_cvt_pk_bf16_f32 v244, v0, v1
	v_cvt_pk_bf16_f32 v245, v2, v3
	v_cvt_pk_bf16_f32 v246, v4, v5
	v_cvt_pk_bf16_f32 v247, v6, v7
	global_store_dwordx2 v234, v[244:245], s[100:101]
	global_store_dwordx2 v235, v[246:247], s[100:101]
	s_add_u32 s100, s100, 0x40000
	s_addc_u32 s101, s101, 0
	ds_write_b16 v172, v70 offset:4096
	ds_write_b16_d16_hi v172, v70 offset:4224
	ds_write_b16 v172, v144 offset:6144
	ds_write_b16_d16_hi v172, v144 offset:6272
	s_and_saveexec_b64 s[20:21], vcc
	ds_write_b64 v163, v[64:65] offset:8320
	ds_write_b64 v163, v[138:139] offset:8384
	s_mov_b64 exec, s[20:21]
	s_waitcnt vmcnt(28)
	ds_write_b64 v28, v[146:147] offset:0
	ds_write_b32 v30, v150 offset:0
	ds_write_b64 v28, v[148:149] offset:5120
	ds_write_b32 v30, v151 offset:2080
	s_waitcnt lgkmcnt(0)
	s_barrier
	ds_read_b128 v[8:11], v29 offset:0
	ds_read_b128 v[12:15], v29 offset:16
	ds_read_b128 v[16:19], v29 offset:32
	ds_read_b128 v[20:23], v29 offset:48
	ds_read_b32 v24, v31 offset:0
	ds_read_b128 v[32:35], v29 offset:5120
	ds_read_b128 v[36:39], v29 offset:5136
	ds_read_b128 v[40:43], v29 offset:5152
	ds_read_b128 v[44:47], v29 offset:5168
	ds_read_b32 v25, v31 offset:2080
	s_sub_u32 s28, s28, 1
	s_cmp_lg_u32 s28, 0
	s_cbranch_scc1 .Lgscan_loop
	global_load_dwordx4 v[178:181], v232, s[34:35]
	global_load_dwordx4 v[182:185], v233, s[34:35]
	global_load_dwordx4 v[186:189], v232, s[34:35] offset:1024
	global_load_dwordx4 v[190:193], v233, s[34:35] offset:1024
	s_add_u32 s34, s34, 0x8000
	s_addc_u32 s35, s35, 0
	global_load_dwordx4 v[194:197], v232, s[34:35]
	global_load_dwordx4 v[198:201], v233, s[34:35]
	global_load_dwordx4 v[202:205], v232, s[34:35] offset:1024
	global_load_dwordx4 v[206:209], v233, s[34:35] offset:1024
	s_add_u32 s34, s34, 0x8000
	s_addc_u32 s35, s35, 0
	ds_read_b128 v[154:157], v75 offset:4096
	ds_read_b128 v[240:243], v164 offset:8320
	ds_read_b128 v[236:239], v75 offset:4160
	s_waitcnt lgkmcnt(3)
; #define MFMA16(a, b, c) __builtin_amdgcn_mfma_f32_16x16x32_bf16((a), (b), (c), 0, 0, 0)
; DI bf16_t f2bf(float x) { return (bf16_t)(pk2(x, 0.f) & 0xffffu); }
; DI float bf2f(unsigned x) { return __uint_as_float(x << 16); }
;     ...
; #pragma unroll
;             for (int e = 0; e < 2; ++e) {
;                 float z = bb[e];
; #pragma unroll
;                 for (int q = 0; q < 4; ++q) { z += a4[q].x * wa[e][4 * q] + a4[q].y * wa[e][4 * q + 1] + a4[q].z * wa[e][4 * q + 2] + a4[q].w * wa[e][4 * q + 3]; }
;                 cum[e] = (fminf(z, 0.f) - __logf(1.f + __expf(-fabsf(z)))) * (1.f / 16.f);
;             }
; #pragma unroll
;             for (int o = 1; o < 64; o <<= 1) {
;                 const float t0 = __shfl_up(cum[0], o), t1 = __shfl_up(cum[1], o);
;                 if (l >= o) { cum[0] += t0; cum[1] += t1; }
;             }
;             const float tot0 = __shfl(cum[0], 63), tot1 = __shfl(cum[1], 63);
;             kdl[(buf * 16 + 2 * w) * 64 + l] = f2bf(bf2f(kraw & 0xffffu) * __expf(tot0 - cum[0]));
;             kdl[(buf * 16 + 2 * w + 1) * 64 + l] = f2bf(bf2f(kraw >> 16) * __expf(tot1 - cum[1]));
;             if (l == 0) { decl[buf * 16 + 2 * w] = __expf(tot0); decl[buf * 16 + 2 * w + 1] = __expf(tot1); }
;             __syncthreads();
;             const f32x4 d4 = *(const f32x4*)(decl + buf * 16 + (l >> 4) * 4);
; #pragma unroll
;             for (int e = 0; e < 2; ++e) acc[e] = acc[e] * d4;
; #pragma unroll
;             for (int ks = 0; ks < 2; ++ks) {
;                 const bf16x8 af = *(const bf16x8*)(kdl + (buf * 16 + (l & 15)) * 64 + ks * 32 + (l >> 4) * 8);
; #pragma unroll
;                 for (int e = 0; e < 2; ++e) acc[e] = MFMA16(af, vfr[e][ks], acc[e]);
	v_pk_fma_f32 v[64:65], v[8:9], v[86:87], v[118:119] op_sel:[0,0,0] op_sel_hi:[0,1,1]
	v_pk_fma_f32 v[138:139], v[32:33], v[86:87], v[118:119] op_sel:[0,0,0] op_sel_hi:[0,1,1]
	v_pk_mul_f32 v[66:67], v[16:17], v[102:103] op_sel:[0,0] op_sel_hi:[0,1]
	v_pk_mul_f32 v[140:141], v[40:41], v[102:103] op_sel:[0,0] op_sel_hi:[0,1]
	v_pk_fma_f32 v[64:65], v[8:9], v[88:89], v[64:65] op_sel:[1,0,0] op_sel_hi:[1,1,1]
	v_pk_fma_f32 v[138:139], v[32:33], v[88:89], v[138:139] op_sel:[1,0,0] op_sel_hi:[1,1,1]
	v_pk_fma_f32 v[66:67], v[16:17], v[104:105], v[66:67] op_sel:[1,0,0] op_sel_hi:[1,1,1]
	v_pk_fma_f32 v[140:141], v[40:41], v[104:105], v[140:141] op_sel:[1,0,0] op_sel_hi:[1,1,1]
	v_pk_fma_f32 v[64:65], v[10:11], v[90:91], v[64:65] op_sel:[0,0,0] op_sel_hi:[0,1,1]
	v_pk_fma_f32 v[138:139], v[34:35], v[90:91], v[138:139] op_sel:[0,0,0] op_sel_hi:[0,1,1]
	v_pk_fma_f32 v[66:67], v[18:19], v[106:107], v[66:67] op_sel:[0,0,0] op_sel_hi:[0,1,1]
	v_pk_fma_f32 v[140:141], v[42:43], v[106:107], v[140:141] op_sel:[0,0,0] op_sel_hi:[0,1,1]
	v_pk_fma_f32 v[64:65], v[10:11], v[92:93], v[64:65] op_sel:[1,0,0] op_sel_hi:[1,1,1]
	v_pk_fma_f32 v[138:139], v[34:35], v[92:93], v[138:139] op_sel:[1,0,0] op_sel_hi:[1,1,1]
	v_pk_fma_f32 v[66:67], v[18:19], v[108:109], v[66:67] op_sel:[1,0,0] op_sel_hi:[1,1,1]
	v_pk_fma_f32 v[140:141], v[42:43], v[108:109], v[140:141] op_sel:[1,0,0] op_sel_hi:[1,1,1]
	v_pk_fma_f32 v[64:65], v[12:13], v[94:95], v[64:65] op_sel:[0,0,0] op_sel_hi:[0,1,1]
	v_pk_fma_f32 v[138:139], v[36:37], v[94:95], v[138:139] op_sel:[0,0,0] op_sel_hi:[0,1,1]
	v_pk_fma_f32 v[66:67], v[20:21], v[110:111], v[66:67] op_sel:[0,0,0] op_sel_hi:[0,1,1]
	v_pk_fma_f32 v[140:141], v[44:45], v[110:111], v[140:141] op_sel:[0,0,0] op_sel_hi:[0,1,1]
	v_pk_fma_f32 v[64:65], v[12:13], v[96:97], v[64:65] op_sel:[1,0,0] op_sel_hi:[1,1,1]
	v_pk_fma_f32 v[138:139], v[36:37], v[96:97], v[138:139] op_sel:[1,0,0] op_sel_hi:[1,1,1]
	v_pk_fma_f32 v[66:67], v[20:21], v[112:113], v[66:67] op_sel:[1,0,0] op_sel_hi:[1,1,1]
	v_pk_fma_f32 v[140:141], v[44:45], v[112:113], v[140:141] op_sel:[1,0,0] op_sel_hi:[1,1,1]
	v_pk_fma_f32 v[64:65], v[14:15], v[98:99], v[64:65] op_sel:[0,0,0] op_sel_hi:[0,1,1]
	v_pk_fma_f32 v[138:139], v[38:39], v[98:99], v[138:139] op_sel:[0,0,0] op_sel_hi:[0,1,1]
	v_pk_fma_f32 v[66:67], v[22:23], v[114:115], v[66:67] op_sel:[0,0,0] op_sel_hi:[0,1,1]
	v_pk_fma_f32 v[140:141], v[46:47], v[114:115], v[140:141] op_sel:[0,0,0] op_sel_hi:[0,1,1]
	v_pk_fma_f32 v[64:65], v[14:15], v[100:101], v[64:65] op_sel:[1,0,0] op_sel_hi:[1,1,1]
	v_pk_fma_f32 v[138:139], v[38:39], v[100:101], v[138:139] op_sel:[1,0,0] op_sel_hi:[1,1,1]
	v_pk_fma_f32 v[66:67], v[22:23], v[116:117], v[66:67] op_sel:[1,0,0] op_sel_hi:[1,1,1]
	v_pk_fma_f32 v[140:141], v[46:47], v[116:117], v[140:141] op_sel:[1,0,0] op_sel_hi:[1,1,1]
	v_pk_add_f32 v[64:65], v[64:65], v[66:67]
	v_pk_add_f32 v[138:139], v[138:139], v[140:141]
	s_waitcnt lgkmcnt(0)
	v_pk_mul_f32 v[0:1], v[0:1], v[240:241]
	v_pk_mul_f32 v[2:3], v[2:3], v[242:243]
	v_pk_mul_f32 v[4:5], v[4:5], v[240:241]
	v_pk_mul_f32 v[6:7], v[6:7], v[242:243]
	s_waitcnt vmcnt(12)
	s_nop 0
	v_mfma_f32_16x16x32_bf16 v[0:3], v[154:157], v[48:51], v[0:3]
	v_mfma_f32_16x16x32_bf16 v[4:7], v[154:157], v[56:59], v[4:7]
	v_mfma_f32_16x16x32_bf16 v[0:3], v[236:239], v[52:55], v[0:3]
	v_mfma_f32_16x16x32_bf16 v[4:7], v[236:239], v[60:63], v[4:7]
	ds_read_b128 v[154:157], v75 offset:6144
	ds_read_b128 v[240:243], v164 offset:8384
	ds_read_b128 v[236:239], v75 offset:6208
	v_mul_f32_e64 v66, |v64|, v220
	v_mul_f32_e64 v140, |v138|, v220
	v_mul_f32_e64 v67, |v65|, v220
	v_mul_f32_e64 v141, |v139|, v220
	v_exp_f32_e32 v66, v66
	v_exp_f32_e32 v140, v140
	v_exp_f32_e32 v67, v67
	v_exp_f32_e32 v141, v141
	v_min_f32_e32 v68, 0, v64
	v_min_f32_e32 v142, 0, v138
	v_min_f32_e32 v69, 0, v65
	v_min_f32_e32 v143, 0, v139
	v_pk_add_f32 v[66:67], v[66:67], v[222:223]
	v_pk_add_f32 v[140:141], v[140:141], v[222:223]
	v_log_f32_e32 v64, v66
	v_log_f32_e32 v138, v140
	v_log_f32_e32 v65, v67
	v_log_f32_e32 v139, v141
	v_pk_mul_f32 v[66:67], v[64:65], v[224:225]
	v_pk_mul_f32 v[140:141], v[138:139], v[224:225]
	v_pk_fma_f32 v[70:71], v[64:65], v[224:225], v[66:67] neg_lo:[0,0,1] neg_hi:[0,0,1]
	v_pk_fma_f32 v[144:145], v[138:139], v[224:225], v[140:141] neg_lo:[0,0,1] neg_hi:[0,0,1]
	v_pk_fma_f32 v[70:71], v[64:65], v[226:227], v[70:71]
	v_pk_fma_f32 v[144:145], v[138:139], v[226:227], v[144:145]
	v_pk_fma_f32 v[70:71], v[64:65], v[224:225], v[70:71]
	v_pk_fma_f32 v[144:145], v[138:139], v[224:225], v[144:145]
	v_pk_add_f32 v[68:69], v[68:69], v[70:71] neg_lo:[0,1] neg_hi:[0,1]
	v_pk_add_f32 v[142:143], v[142:143], v[144:145] neg_lo:[0,1] neg_hi:[0,1]
	v_pk_mul_f32 v[68:69], v[68:69], v[214:215]
	v_pk_mul_f32 v[142:143], v[142:143], v[214:215]
	v_cvt_pk_bf16_f32 v244, v0, v1
	v_cvt_pk_bf16_f32 v245, v2, v3
	v_cvt_pk_bf16_f32 v246, v4, v5
	v_cvt_pk_bf16_f32 v247, v6, v7
	global_store_dwordx2 v234, v[244:245], s[100:101]
	global_store_dwordx2 v235, v[246:247], s[100:101]
	s_add_u32 s100, s100, 0x40000
	s_addc_u32 s101, s101, 0
	s_waitcnt lgkmcnt(0)
	v_pk_mul_f32 v[0:1], v[0:1], v[240:241]
	v_pk_mul_f32 v[2:3], v[2:3], v[242:243]
	v_pk_mul_f32 v[4:5], v[4:5], v[240:241]
	v_pk_mul_f32 v[6:7], v[6:7], v[242:243]
	s_waitcnt vmcnt(14)
; DI float bf2f(unsigned x) { return __uint_as_float(x << 16); }
;     ...
;         auto ldchunk = [&](int n) {
;             const int tok = b * 4096 + n * 64 + l;
; #pragma unroll
;             for (int q = 0; q < 4; ++q) a4n[q] = *(const f32x4*)(GA + (size_t)tok * 16 + 4 * q);
;             krawn = *(const unsigned*)(GK + (size_t)tok * 512 + kc0);
; #pragma unroll
;             for (int e = 0; e < 2; ++e)
; #pragma unroll
;                 for (int ks = 0; ks < 2; ++ks)
;                     vfrn[e][ks] = *(const bf16x8*)(GVT + ((size_t)(b * 1024 + hh * 256 + (2 * w + e) * 16 + (l & 15))) * 4096 + n * 64 + ks * 32 + (l >> 4) * 8);
;         };
;         ldchunk(0);
;         for (int n = 0; n < 64; ++n) {
;             const int buf = n & 1;
;             f32x4 a4[4]; bf16x8 vfr[2][2];
; #pragma unroll
;             for (int q = 0; q < 4; ++q) a4[q] = a4n[q];
;             const unsigned kraw = krawn;
; #pragma unroll
;             for (int e = 0; e < 2; ++e)
; #pragma unroll
;                 for (int ks = 0; ks < 2; ++ks) vfr[e][ks] = vfrn[e][ks];
;             if (n + 1 < 64) ldchunk(n + 1);
;             float cum[2];
; #pragma unroll
;             for (int e = 0; e < 2; ++e) {
;                 float z = bb[e];
; #pragma unroll
;                 for (int q = 0; q < 4; ++q) { z += a4[q].x * wa[e][4 * q] + a4[q].y * wa[e][4 * q + 1] + a4[q].z * wa[e][4 * q + 2] + a4[q].w * wa[e][4 * q + 3]; }
;                 cum[e] = (fminf(z, 0.f) - __logf(1.f + __expf(-fabsf(z)))) * (1.f / 16.f);
;             }
; #pragma unroll
;             for (int o = 1; o < 64; o <<= 1) {
;                 const float t0 = __shfl_up(cum[0], o), t1 = __shfl_up(cum[1], o);
;                 if (l >= o) { cum[0] += t0; cum[1] += t1; }
;             }
;             const float tot0 = __shfl(cum[0], 63), tot1 = __shfl(cum[1], 63);
;             kdl[(buf * 16 + 2 * w) * 64 + l] = f2bf(bf2f(kraw & 0xffffu) * __expf(tot0 - cum[0]));
;             kdl[(buf * 16 + 2 * w + 1) * 64 + l] = f2bf(bf2f(kraw >> 16) * __expf(tot1 - cum[1]));
;             if (l == 0) { decl[buf * 16 + 2 * w] = __expf(tot0); decl[buf * 16 + 2 * w + 1] = __expf(tot1); }
;             __syncthreads();
;             const f32x4 d4 = *(const f32x4*)(decl + buf * 16 + (l >> 4) * 4);
; #pragma unroll
;             for (int e = 0; e < 2; ++e) acc[e] = acc[e] * d4;
; #pragma unroll
;             for (int ks = 0; ks < 2; ++ks) {
	s_nop 0
	v_mfma_f32_16x16x32_bf16 v[0:3], v[154:157], v[122:125], v[0:3]
	v_mfma_f32_16x16x32_bf16 v[4:7], v[154:157], v[130:133], v[4:7]
	v_mfma_f32_16x16x32_bf16 v[0:3], v[236:239], v[126:129], v[0:3]
	v_mfma_f32_16x16x32_bf16 v[4:7], v[236:239], v[134:137], v[4:7]
	v_add_f32_dpp v68, v68, v68 row_shr:1 row_mask:0xf bank_mask:0xf
	v_add_f32_dpp v142, v142, v142 row_shr:1 row_mask:0xf bank_mask:0xf
	v_add_f32_dpp v69, v69, v69 row_shr:1 row_mask:0xf bank_mask:0xf
	v_add_f32_dpp v143, v143, v143 row_shr:1 row_mask:0xf bank_mask:0xf
	v_add_f32_dpp v68, v68, v68 row_shr:2 row_mask:0xf bank_mask:0xf
	v_add_f32_dpp v142, v142, v142 row_shr:2 row_mask:0xf bank_mask:0xf
	v_add_f32_dpp v69, v69, v69 row_shr:2 row_mask:0xf bank_mask:0xf
	v_add_f32_dpp v143, v143, v143 row_shr:2 row_mask:0xf bank_mask:0xf
	v_add_f32_dpp v68, v68, v68 row_shr:4 row_mask:0xf bank_mask:0xf
	v_add_f32_dpp v142, v142, v142 row_shr:4 row_mask:0xf bank_mask:0xf
	v_add_f32_dpp v69, v69, v69 row_shr:4 row_mask:0xf bank_mask:0xf
	v_add_f32_dpp v143, v143, v143 row_shr:4 row_mask:0xf bank_mask:0xf
	v_add_f32_dpp v68, v68, v68 row_shr:8 row_mask:0xf bank_mask:0xf
	v_add_f32_dpp v142, v142, v142 row_shr:8 row_mask:0xf bank_mask:0xf
	v_add_f32_dpp v69, v69, v69 row_shr:8 row_mask:0xf bank_mask:0xf
	v_add_f32_dpp v143, v143, v143 row_shr:8 row_mask:0xf bank_mask:0xf
	v_add_f32_dpp v68, v68, v68 row_bcast:15 row_mask:0xa bank_mask:0xf
	v_add_f32_dpp v142, v142, v142 row_bcast:15 row_mask:0xa bank_mask:0xf
	v_add_f32_dpp v69, v69, v69 row_bcast:15 row_mask:0xa bank_mask:0xf
	v_add_f32_dpp v143, v143, v143 row_bcast:15 row_mask:0xa bank_mask:0xf
	v_add_f32_dpp v68, v68, v68 row_bcast:31 row_mask:0xc bank_mask:0xf
	v_add_f32_dpp v142, v142, v142 row_bcast:31 row_mask:0xc bank_mask:0xf
	v_add_f32_dpp v69, v69, v69 row_bcast:31 row_mask:0xc bank_mask:0xf
	v_add_f32_dpp v143, v143, v143 row_bcast:31 row_mask:0xc bank_mask:0xf
	v_readlane_b32 s98, v68, 63
	v_readlane_b32 s52, v142, 63
	v_readlane_b32 s99, v69, 63
	v_readlane_b32 s53, v143, 63
	s_nop 0
	v_pk_add_f32 v[66:67], s[98:99], v[68:69] neg_lo:[0,1] neg_hi:[0,1]
	v_pk_add_f32 v[140:141], s[52:53], v[142:143] neg_lo:[0,1] neg_hi:[0,1]
	v_mul_f32_e64 v64, s98, v228
	v_mul_f32_e64 v138, s52, v228
	v_mul_f32_e64 v65, s99, v228
	v_mul_f32_e64 v139, s53, v228
	v_pk_mul_f32 v[66:67], v[66:67], v[228:229]
	v_pk_mul_f32 v[140:141], v[140:141], v[228:229]
	v_exp_f32_e32 v64, v64
	v_exp_f32_e32 v138, v138
	v_exp_f32_e32 v65, v65
	v_exp_f32_e32 v139, v139
	v_exp_f32_e32 v66, v66
	v_exp_f32_e32 v140, v140
	v_exp_f32_e32 v67, v67
	v_exp_f32_e32 v141, v141
	v_lshlrev_b32_e32 v70, 16, v24
	v_lshlrev_b32_e32 v144, 16, v25
	v_and_b32_e32 v71, 0xffff0000, v24
	v_and_b32_e32 v145, 0xffff0000, v25
	v_pk_mul_f32 v[66:67], v[66:67], v[70:71]
	v_pk_mul_f32 v[140:141], v[140:141], v[144:145]
	v_cvt_pk_bf16_f32 v70, v66, v67
	v_cvt_pk_bf16_f32 v144, v140, v141
	v_cvt_pk_bf16_f32 v244, v0, v1
	v_cvt_pk_bf16_f32 v245, v2, v3
	v_cvt_pk_bf16_f32 v246, v4, v5
	v_cvt_pk_bf16_f32 v247, v6, v7
	global_store_dwordx2 v234, v[244:245], s[100:101]
	global_store_dwordx2 v235, v[246:247], s[100:101]
	s_add_u32 s100, s100, 0x40000
	s_addc_u32 s101, s101, 0
	ds_write_b16 v172, v70 offset:0
	ds_write_b16_d16_hi v172, v70 offset:128
	ds_write_b16 v172, v144 offset:2048
	ds_write_b16_d16_hi v172, v144 offset:2176
	s_and_saveexec_b64 s[20:21], vcc
	ds_write_b64 v163, v[64:65] offset:8192
	ds_write_b64 v163, v[138:139] offset:8256
	s_mov_b64 exec, s[20:21]
	s_waitcnt vmcnt(24)
	ds_write_b64 v28, v[152:153] offset:10240
	ds_write_b32 v30, v158 offset:4160
	ds_write_b64 v28, v[166:167] offset:15360
	ds_write_b32 v30, v159 offset:6240
	s_waitcnt lgkmcnt(0)
	s_barrier
	ds_read_b128 v[8:11], v29 offset:10240
	ds_read_b128 v[12:15], v29 offset:10256
	ds_read_b128 v[16:19], v29 offset:10272
	ds_read_b128 v[20:23], v29 offset:10288
	ds_read_b32 v24, v31 offset:4160
	ds_read_b128 v[32:35], v29 offset:15360
	ds_read_b128 v[36:39], v29 offset:15376
	ds_read_b128 v[40:43], v29 offset:15392
	ds_read_b128 v[44:47], v29 offset:15408
	ds_read_b32 v25, v31 offset:6240
	global_load_dwordx4 v[48:51], v232, s[34:35]
	global_load_dwordx4 v[52:55], v233, s[34:35]
	global_load_dwordx4 v[56:59], v232, s[34:35] offset:1024
	global_load_dwordx4 v[60:63], v233, s[34:35] offset:1024
	s_add_u32 s34, s34, 0x8000
	s_addc_u32 s35, s35, 0
	global_load_dwordx4 v[122:125], v232, s[34:35]
	global_load_dwordx4 v[126:129], v233, s[34:35]
	global_load_dwordx4 v[130:133], v232, s[34:35] offset:1024
	global_load_dwordx4 v[134:137], v233, s[34:35] offset:1024
	s_add_u32 s34, s34, 0x8000
	s_addc_u32 s35, s35, 0
	ds_read_b128 v[154:157], v75 offset:0
	ds_read_b128 v[240:243], v164 offset:8192
	ds_read_b128 v[236:239], v75 offset:64
	s_waitcnt lgkmcnt(3)
; #define MFMA16(a, b, c) __builtin_amdgcn_mfma_f32_16x16x32_bf16((a), (b), (c), 0, 0, 0)
; DI bf16_t f2bf(float x) { return (bf16_t)(pk2(x, 0.f) & 0xffffu); }
; DI float bf2f(unsigned x) { return __uint_as_float(x << 16); }
;     ...
; #pragma unroll
;             for (int e = 0; e < 2; ++e) {
;                 float z = bb[e];
; #pragma unroll
;                 for (int q = 0; q < 4; ++q) { z += a4[q].x * wa[e][4 * q] + a4[q].y * wa[e][4 * q + 1] + a4[q].z * wa[e][4 * q + 2] + a4[q].w * wa[e][4 * q + 3]; }
;                 cum[e] = (fminf(z, 0.f) - __logf(1.f + __expf(-fabsf(z)))) * (1.f / 16.f);
;             }
; #pragma unroll
;             for (int o = 1; o < 64; o <<= 1) {
;                 const float t0 = __shfl_up(cum[0], o), t1 = __shfl_up(cum[1], o);
;                 if (l >= o) { cum[0] += t0; cum[1] += t1; }
;             }
;             const float tot0 = __shfl(cum[0], 63), tot1 = __shfl(cum[1], 63);
;             kdl[(buf * 16 + 2 * w) * 64 + l] = f2bf(bf2f(kraw & 0xffffu) * __expf(tot0 - cum[0]));
;             kdl[(buf * 16 + 2 * w + 1) * 64 + l] = f2bf(bf2f(kraw >> 16) * __expf(tot1 - cum[1]));
;             if (l == 0) { decl[buf * 16 + 2 * w] = __expf(tot0); decl[buf * 16 + 2 * w + 1] = __expf(tot1); }
;             __syncthreads();
;             const f32x4 d4 = *(const f32x4*)(decl + buf * 16 + (l >> 4) * 4);
; #pragma unroll
;             for (int e = 0; e < 2; ++e) acc[e] = acc[e] * d4;
; #pragma unroll
;             for (int ks = 0; ks < 2; ++ks) {
;                 const bf16x8 af = *(const bf16x8*)(kdl + (buf * 16 + (l & 15)) * 64 + ks * 32 + (l >> 4) * 8);
; #pragma unroll
;                 for (int e = 0; e < 2; ++e) acc[e] = MFMA16(af, vfr[e][ks], acc[e]);
	v_pk_fma_f32 v[64:65], v[8:9], v[86:87], v[118:119] op_sel:[0,0,0] op_sel_hi:[0,1,1]
	v_pk_fma_f32 v[138:139], v[32:33], v[86:87], v[118:119] op_sel:[0,0,0] op_sel_hi:[0,1,1]
	v_pk_mul_f32 v[66:67], v[16:17], v[102:103] op_sel:[0,0] op_sel_hi:[0,1]
	v_pk_mul_f32 v[140:141], v[40:41], v[102:103] op_sel:[0,0] op_sel_hi:[0,1]
	v_pk_fma_f32 v[64:65], v[8:9], v[88:89], v[64:65] op_sel:[1,0,0] op_sel_hi:[1,1,1]
	v_pk_fma_f32 v[138:139], v[32:33], v[88:89], v[138:139] op_sel:[1,0,0] op_sel_hi:[1,1,1]
	v_pk_fma_f32 v[66:67], v[16:17], v[104:105], v[66:67] op_sel:[1,0,0] op_sel_hi:[1,1,1]
	v_pk_fma_f32 v[140:141], v[40:41], v[104:105], v[140:141] op_sel:[1,0,0] op_sel_hi:[1,1,1]
	v_pk_fma_f32 v[64:65], v[10:11], v[90:91], v[64:65] op_sel:[0,0,0] op_sel_hi:[0,1,1]
	v_pk_fma_f32 v[138:139], v[34:35], v[90:91], v[138:139] op_sel:[0,0,0] op_sel_hi:[0,1,1]
	v_pk_fma_f32 v[66:67], v[18:19], v[106:107], v[66:67] op_sel:[0,0,0] op_sel_hi:[0,1,1]
	v_pk_fma_f32 v[140:141], v[42:43], v[106:107], v[140:141] op_sel:[0,0,0] op_sel_hi:[0,1,1]
	v_pk_fma_f32 v[64:65], v[10:11], v[92:93], v[64:65] op_sel:[1,0,0] op_sel_hi:[1,1,1]
	v_pk_fma_f32 v[138:139], v[34:35], v[92:93], v[138:139] op_sel:[1,0,0] op_sel_hi:[1,1,1]
	v_pk_fma_f32 v[66:67], v[18:19], v[108:109], v[66:67] op_sel:[1,0,0] op_sel_hi:[1,1,1]
	v_pk_fma_f32 v[140:141], v[42:43], v[108:109], v[140:141] op_sel:[1,0,0] op_sel_hi:[1,1,1]
	v_pk_fma_f32 v[64:65], v[12:13], v[94:95], v[64:65] op_sel:[0,0,0] op_sel_hi:[0,1,1]
	v_pk_fma_f32 v[138:139], v[36:37], v[94:95], v[138:139] op_sel:[0,0,0] op_sel_hi:[0,1,1]
	v_pk_fma_f32 v[66:67], v[20:21], v[110:111], v[66:67] op_sel:[0,0,0] op_sel_hi:[0,1,1]
	v_pk_fma_f32 v[140:141], v[44:45], v[110:111], v[140:141] op_sel:[0,0,0] op_sel_hi:[0,1,1]
	v_pk_fma_f32 v[64:65], v[12:13], v[96:97], v[64:65] op_sel:[1,0,0] op_sel_hi:[1,1,1]
	v_pk_fma_f32 v[138:139], v[36:37], v[96:97], v[138:139] op_sel:[1,0,0] op_sel_hi:[1,1,1]
	v_pk_fma_f32 v[66:67], v[20:21], v[112:113], v[66:67] op_sel:[1,0,0] op_sel_hi:[1,1,1]
	v_pk_fma_f32 v[140:141], v[44:45], v[112:113], v[140:141] op_sel:[1,0,0] op_sel_hi:[1,1,1]
	v_pk_fma_f32 v[64:65], v[14:15], v[98:99], v[64:65] op_sel:[0,0,0] op_sel_hi:[0,1,1]
	v_pk_fma_f32 v[138:139], v[38:39], v[98:99], v[138:139] op_sel:[0,0,0] op_sel_hi:[0,1,1]
	v_pk_fma_f32 v[66:67], v[22:23], v[114:115], v[66:67] op_sel:[0,0,0] op_sel_hi:[0,1,1]
	v_pk_fma_f32 v[140:141], v[46:47], v[114:115], v[140:141] op_sel:[0,0,0] op_sel_hi:[0,1,1]
	v_pk_fma_f32 v[64:65], v[14:15], v[100:101], v[64:65] op_sel:[1,0,0] op_sel_hi:[1,1,1]
	v_pk_fma_f32 v[138:139], v[38:39], v[100:101], v[138:139] op_sel:[1,0,0] op_sel_hi:[1,1,1]
	v_pk_fma_f32 v[66:67], v[22:23], v[116:117], v[66:67] op_sel:[1,0,0] op_sel_hi:[1,1,1]
	v_pk_fma_f32 v[140:141], v[46:47], v[116:117], v[140:141] op_sel:[1,0,0] op_sel_hi:[1,1,1]
	v_pk_add_f32 v[64:65], v[64:65], v[66:67]
	v_pk_add_f32 v[138:139], v[138:139], v[140:141]
	s_waitcnt lgkmcnt(0)
	v_pk_mul_f32 v[0:1], v[0:1], v[240:241]
	v_pk_mul_f32 v[2:3], v[2:3], v[242:243]
	v_pk_mul_f32 v[4:5], v[4:5], v[240:241]
	v_pk_mul_f32 v[6:7], v[6:7], v[242:243]
	s_waitcnt vmcnt(12)
	s_nop 0
	v_mfma_f32_16x16x32_bf16 v[0:3], v[154:157], v[178:181], v[0:3]
	v_mfma_f32_16x16x32_bf16 v[4:7], v[154:157], v[186:189], v[4:7]
	v_mfma_f32_16x16x32_bf16 v[0:3], v[236:239], v[182:185], v[0:3]
	v_mfma_f32_16x16x32_bf16 v[4:7], v[236:239], v[190:193], v[4:7]
	ds_read_b128 v[154:157], v75 offset:2048
	ds_read_b128 v[240:243], v164 offset:8256
	ds_read_b128 v[236:239], v75 offset:2112
	v_mul_f32_e64 v66, |v64|, v220
	v_mul_f32_e64 v140, |v138|, v220
	v_mul_f32_e64 v67, |v65|, v220
	v_mul_f32_e64 v141, |v139|, v220
	v_exp_f32_e32 v66, v66
	v_exp_f32_e32 v140, v140
	v_exp_f32_e32 v67, v67
	v_exp_f32_e32 v141, v141
	v_min_f32_e32 v68, 0, v64
	v_min_f32_e32 v142, 0, v138
	v_min_f32_e32 v69, 0, v65
	v_min_f32_e32 v143, 0, v139
	v_pk_add_f32 v[66:67], v[66:67], v[222:223]
	v_pk_add_f32 v[140:141], v[140:141], v[222:223]
	v_log_f32_e32 v64, v66
	v_log_f32_e32 v138, v140
	v_log_f32_e32 v65, v67
	v_log_f32_e32 v139, v141
	v_pk_mul_f32 v[66:67], v[64:65], v[224:225]
	v_pk_mul_f32 v[140:141], v[138:139], v[224:225]
	v_pk_fma_f32 v[70:71], v[64:65], v[224:225], v[66:67] neg_lo:[0,0,1] neg_hi:[0,0,1]
	v_pk_fma_f32 v[144:145], v[138:139], v[224:225], v[140:141] neg_lo:[0,0,1] neg_hi:[0,0,1]
	v_pk_fma_f32 v[70:71], v[64:65], v[226:227], v[70:71]
	v_pk_fma_f32 v[144:145], v[138:139], v[226:227], v[144:145]
	v_pk_fma_f32 v[70:71], v[64:65], v[224:225], v[70:71]
	v_pk_fma_f32 v[144:145], v[138:139], v[224:225], v[144:145]
	v_pk_add_f32 v[68:69], v[68:69], v[70:71] neg_lo:[0,1] neg_hi:[0,1]
	v_pk_add_f32 v[142:143], v[142:143], v[144:145] neg_lo:[0,1] neg_hi:[0,1]
	v_pk_mul_f32 v[68:69], v[68:69], v[214:215]
	v_pk_mul_f32 v[142:143], v[142:143], v[214:215]
	v_cvt_pk_bf16_f32 v244, v0, v1
	v_cvt_pk_bf16_f32 v245, v2, v3
	v_cvt_pk_bf16_f32 v246, v4, v5
	v_cvt_pk_bf16_f32 v247, v6, v7
	global_store_dwordx2 v234, v[244:245], s[100:101]
	global_store_dwordx2 v235, v[246:247], s[100:101]
	s_add_u32 s100, s100, 0x40000
	s_addc_u32 s101, s101, 0
	s_waitcnt lgkmcnt(0)
	v_pk_mul_f32 v[0:1], v[0:1], v[240:241]
	v_pk_mul_f32 v[2:3], v[2:3], v[242:243]
	v_pk_mul_f32 v[4:5], v[4:5], v[240:241]
	v_pk_mul_f32 v[6:7], v[6:7], v[242:243]
	s_waitcnt vmcnt(14)
; #define MFMA16(a, b, c) __builtin_amdgcn_mfma_f32_16x16x32_bf16((a), (b), (c), 0, 0, 0)
; DI bf16_t f2bf(float x) { return (bf16_t)(pk2(x, 0.f) & 0xffffu); }
; DI float bf2f(unsigned x) { return __uint_as_float(x << 16); }
; DI u32x2 pk4(float a, float b, float c, float d) { u32x2 r; r.x = pk2(a, b); r.y = pk2(c, d); return r; }
;     ...
; #pragma unroll
;             for (int o = 1; o < 64; o <<= 1) {
;                 const float t0 = __shfl_up(cum[0], o), t1 = __shfl_up(cum[1], o);
;                 if (l >= o) { cum[0] += t0; cum[1] += t1; }
;             }
;             const float tot0 = __shfl(cum[0], 63), tot1 = __shfl(cum[1], 63);
;             kdl[(buf * 16 + 2 * w) * 64 + l] = f2bf(bf2f(kraw & 0xffffu) * __expf(tot0 - cum[0]));
;             kdl[(buf * 16 + 2 * w + 1) * 64 + l] = f2bf(bf2f(kraw >> 16) * __expf(tot1 - cum[1]));
;             if (l == 0) { decl[buf * 16 + 2 * w] = __expf(tot0); decl[buf * 16 + 2 * w + 1] = __expf(tot1); }
;             __syncthreads();
;             const f32x4 d4 = *(const f32x4*)(decl + buf * 16 + (l >> 4) * 4);
; #pragma unroll
;             for (int e = 0; e < 2; ++e) acc[e] = acc[e] * d4;
; #pragma unroll
;             for (int ks = 0; ks < 2; ++ks) {
;                 const bf16x8 af = *(const bf16x8*)(kdl + (buf * 16 + (l & 15)) * 64 + ks * 32 + (l >> 4) * 8);
; #pragma unroll
;                 for (int e = 0; e < 2; ++e) acc[e] = MFMA16(af, vfr[e][ks], acc[e]);
;             }
;             const int cidx = b * 64 + n;
; #pragma unroll
;             for (int e = 0; e < 2; ++e) {
;                 const int vv = (2 * w + e) * 16 + (l & 15);
;                 *(u32x2*)(ST + (((size_t)(cidx * 4 + hh)) * 256 + vv) * 128 + ksl * 16 + (l >> 4) * 4) = pk4(acc[e].x, acc[e].y, acc[e].z, acc[e].w);
;             }
;         }
	s_nop 0
	v_mfma_f32_16x16x32_bf16 v[0:3], v[154:157], v[194:197], v[0:3]
	v_mfma_f32_16x16x32_bf16 v[4:7], v[154:157], v[202:205], v[4:7]
	v_mfma_f32_16x16x32_bf16 v[0:3], v[236:239], v[198:201], v[0:3]
	v_mfma_f32_16x16x32_bf16 v[4:7], v[236:239], v[206:209], v[4:7]
	v_add_f32_dpp v68, v68, v68 row_shr:1 row_mask:0xf bank_mask:0xf
	v_add_f32_dpp v142, v142, v142 row_shr:1 row_mask:0xf bank_mask:0xf
	v_add_f32_dpp v69, v69, v69 row_shr:1 row_mask:0xf bank_mask:0xf
	v_add_f32_dpp v143, v143, v143 row_shr:1 row_mask:0xf bank_mask:0xf
	v_add_f32_dpp v68, v68, v68 row_shr:2 row_mask:0xf bank_mask:0xf
	v_add_f32_dpp v142, v142, v142 row_shr:2 row_mask:0xf bank_mask:0xf
	v_add_f32_dpp v69, v69, v69 row_shr:2 row_mask:0xf bank_mask:0xf
	v_add_f32_dpp v143, v143, v143 row_shr:2 row_mask:0xf bank_mask:0xf
	v_add_f32_dpp v68, v68, v68 row_shr:4 row_mask:0xf bank_mask:0xf
	v_add_f32_dpp v142, v142, v142 row_shr:4 row_mask:0xf bank_mask:0xf
	v_add_f32_dpp v69, v69, v69 row_shr:4 row_mask:0xf bank_mask:0xf
	v_add_f32_dpp v143, v143, v143 row_shr:4 row_mask:0xf bank_mask:0xf
	v_add_f32_dpp v68, v68, v68 row_shr:8 row_mask:0xf bank_mask:0xf
	v_add_f32_dpp v142, v142, v142 row_shr:8 row_mask:0xf bank_mask:0xf
	v_add_f32_dpp v69, v69, v69 row_shr:8 row_mask:0xf bank_mask:0xf
	v_add_f32_dpp v143, v143, v143 row_shr:8 row_mask:0xf bank_mask:0xf
	v_add_f32_dpp v68, v68, v68 row_bcast:15 row_mask:0xa bank_mask:0xf
	v_add_f32_dpp v142, v142, v142 row_bcast:15 row_mask:0xa bank_mask:0xf
	v_add_f32_dpp v69, v69, v69 row_bcast:15 row_mask:0xa bank_mask:0xf
	v_add_f32_dpp v143, v143, v143 row_bcast:15 row_mask:0xa bank_mask:0xf
	v_add_f32_dpp v68, v68, v68 row_bcast:31 row_mask:0xc bank_mask:0xf
	v_add_f32_dpp v142, v142, v142 row_bcast:31 row_mask:0xc bank_mask:0xf
	v_add_f32_dpp v69, v69, v69 row_bcast:31 row_mask:0xc bank_mask:0xf
	v_add_f32_dpp v143, v143, v143 row_bcast:31 row_mask:0xc bank_mask:0xf
	v_readlane_b32 s98, v68, 63
	v_readlane_b32 s52, v142, 63
	v_readlane_b32 s99, v69, 63
	v_readlane_b32 s53, v143, 63
	s_nop 0
	v_pk_add_f32 v[66:67], s[98:99], v[68:69] neg_lo:[0,1] neg_hi:[0,1]
	v_pk_add_f32 v[140:141], s[52:53], v[142:143] neg_lo:[0,1] neg_hi:[0,1]
	v_mul_f32_e64 v64, s98, v228
	v_mul_f32_e64 v138, s52, v228
	v_mul_f32_e64 v65, s99, v228
	v_mul_f32_e64 v139, s53, v228
	v_pk_mul_f32 v[66:67], v[66:67], v[228:229]
	v_pk_mul_f32 v[140:141], v[140:141], v[228:229]
	v_exp_f32_e32 v64, v64
	v_exp_f32_e32 v138, v138
	v_exp_f32_e32 v65, v65
	v_exp_f32_e32 v139, v139
	v_exp_f32_e32 v66, v66
	v_exp_f32_e32 v140, v140
	v_exp_f32_e32 v67, v67
	v_exp_f32_e32 v141, v141
	v_lshlrev_b32_e32 v70, 16, v24
	v_lshlrev_b32_e32 v144, 16, v25
	v_and_b32_e32 v71, 0xffff0000, v24
	v_and_b32_e32 v145, 0xffff0000, v25
	v_pk_mul_f32 v[66:67], v[66:67], v[70:71]
	v_pk_mul_f32 v[140:141], v[140:141], v[144:145]
	v_cvt_pk_bf16_f32 v70, v66, v67
	v_cvt_pk_bf16_f32 v144, v140, v141
	v_cvt_pk_bf16_f32 v244, v0, v1
	v_cvt_pk_bf16_f32 v245, v2, v3
	v_cvt_pk_bf16_f32 v246, v4, v5
	v_cvt_pk_bf16_f32 v247, v6, v7
	global_store_dwordx2 v234, v[244:245], s[100:101]
	global_store_dwordx2 v235, v[246:247], s[100:101]
	s_add_u32 s100, s100, 0x40000
	s_addc_u32 s101, s101, 0
	ds_write_b16 v172, v70 offset:4096
	ds_write_b16_d16_hi v172, v70 offset:4224
	ds_write_b16 v172, v144 offset:6144
	ds_write_b16_d16_hi v172, v144 offset:6272
	s_and_saveexec_b64 s[20:21], vcc
	ds_write_b64 v163, v[64:65] offset:8320
	ds_write_b64 v163, v[138:139] offset:8384
	s_mov_b64 exec, s[20:21]
	s_waitcnt lgkmcnt(0)
	s_barrier
	ds_read_b128 v[154:157], v75 offset:4096
	ds_read_b128 v[240:243], v164 offset:8320
	ds_read_b128 v[236:239], v75 offset:4160
	s_waitcnt lgkmcnt(0)
	v_pk_mul_f32 v[0:1], v[0:1], v[240:241]
	v_pk_mul_f32 v[2:3], v[2:3], v[242:243]
	v_pk_mul_f32 v[4:5], v[4:5], v[240:241]
	v_pk_mul_f32 v[6:7], v[6:7], v[242:243]
	s_waitcnt vmcnt(4)
	s_nop 0
	v_mfma_f32_16x16x32_bf16 v[0:3], v[154:157], v[48:51], v[0:3]
	v_mfma_f32_16x16x32_bf16 v[4:7], v[154:157], v[56:59], v[4:7]
	v_mfma_f32_16x16x32_bf16 v[0:3], v[236:239], v[52:55], v[0:3]
	v_mfma_f32_16x16x32_bf16 v[4:7], v[236:239], v[60:63], v[4:7]
	ds_read_b128 v[154:157], v75 offset:6144
	ds_read_b128 v[240:243], v164 offset:8384
	ds_read_b128 v[236:239], v75 offset:6208
	s_nop 7
	s_nop 1
	v_cvt_pk_bf16_f32 v244, v0, v1
	v_cvt_pk_bf16_f32 v245, v2, v3
	v_cvt_pk_bf16_f32 v246, v4, v5
	v_cvt_pk_bf16_f32 v247, v6, v7
	global_store_dwordx2 v234, v[244:245], s[100:101]
	global_store_dwordx2 v235, v[246:247], s[100:101]
	s_add_u32 s100, s100, 0x40000
	s_addc_u32 s101, s101, 0
	s_waitcnt lgkmcnt(0)
	v_pk_mul_f32 v[0:1], v[0:1], v[240:241]
	v_pk_mul_f32 v[2:3], v[2:3], v[242:243]
	v_pk_mul_f32 v[4:5], v[4:5], v[240:241]
	v_pk_mul_f32 v[6:7], v[6:7], v[242:243]
	s_waitcnt vmcnt(6)
	s_nop 0
	v_mfma_f32_16x16x32_bf16 v[0:3], v[154:157], v[122:125], v[0:3]
	v_mfma_f32_16x16x32_bf16 v[4:7], v[154:157], v[130:133], v[4:7]
	v_mfma_f32_16x16x32_bf16 v[0:3], v[236:239], v[126:129], v[0:3]
	v_mfma_f32_16x16x32_bf16 v[4:7], v[236:239], v[134:137], v[4:7]
	s_nop 7
	s_nop 1
	v_cvt_pk_bf16_f32 v244, v0, v1
	v_cvt_pk_bf16_f32 v245, v2, v3
	v_cvt_pk_bf16_f32 v246, v4, v5
	v_cvt_pk_bf16_f32 v247, v6, v7
	global_store_dwordx2 v234, v[244:245], s[100:101]
	global_store_dwordx2 v235, v[246:247], s[100:101]
	s_add_u32 s100, s100, 0x40000
	s_addc_u32 s101, s101, 0
	s_add_i32 s56, s56, s96
	s_cmpk_gt_i32 s56, 0xff
	s_cbranch_scc0 .LBB0_418
